# W_out^T also stored chunk-swizzled; P5 main and small-tile K-loops read B through the map (small-tile loop now issues its whole prologue itself)
# speedup vs baseline: 1.0131x; 1.0028x over previous
.Ltr_p_d3:
	s_lshr_b32 s6, s5, 5
	s_and_b32 s7, s5, 31
	s_mov_b32 s12, 0x2000
	s_movk_i32 s13, 31
	s_mul_i32 s8, s6, 0x80000
	s_lshl_b32 s9, s7, 8
	s_add_u32 s8, s8, s9
	s_add_u32 s10, s36, s8
	s_addc_u32 s11, s37, 0
	s_lshl_b32 s8, s7, 18
	s_add_u32 s8, s8, 0x18a88000
	s_add_u32 s14, s94, s8
	s_addc_u32 s15, s95, 0
	s_branch .Ltr_p_end

.LBB0_707:
	v_add_u32_e32 v0, v206, v207
	s_movk_i32 s22, 0x1ff
	v_cmp_lt_i32_e32 vcc, s22, v0
	s_cbranch_vccnz .LBB0_706
	v_readfirstlane_b32 s22, v0
	s_ashr_i32 s23, s22, 31
	s_lshr_b32 s23, s23, 25
	s_add_i32 s23, s22, s23
	s_ashr_i32 s33, s23, 7
	s_lshl_b32 s41, s33, 3
	s_and_b32 s23, s23, 0xffffff80
	s_sub_i32 s40, 32, s41
	s_cmpk_gt_i32 s22, 0x1ff
	s_cselect_b32 s42, s40, 8
	s_abs_i32 s40, s42
	v_cvt_f32_u32_e32 v1, s40
	v_subrev_u32_e32 v0, s23, v0
	s_sub_i32 s23, 0, s40
	v_sub_u32_e32 v2, 0, v0
	v_rcp_iflag_f32_e32 v1, v1
	v_max_i32_e32 v2, v0, v2
	v_xor_b32_e32 v3, s42, v0
	v_ashrrev_i32_e32 v3, 31, v3
	v_mul_f32_e32 v1, 0x4f7ffffe, v1
	v_cvt_u32_f32_e32 v1, v1
	v_mov_b32_e32 v8, v204
	s_mulk_i32 s33, 0x78
	v_mul_lo_u32 v4, s23, v1
	v_mul_hi_u32 v4, v1, v4
	v_add_u32_e32 v1, v1, v4
	v_mul_hi_u32 v1, v2, v1
	v_mul_lo_u32 v4, v1, s40
	v_sub_u32_e32 v2, v2, v4
	v_add_u32_e32 v5, 1, v1
	v_subrev_u32_e32 v4, s40, v2
	v_cmp_le_u32_e32 vcc, s40, v2
	s_mov_b32 s22, 0
	s_nop 0
	v_cndmask_b32_e32 v1, v1, v5, vcc
	v_cndmask_b32_e32 v2, v2, v4, vcc
	v_add_u32_e32 v4, 1, v1
	v_cmp_le_u32_e32 vcc, s40, v2
	v_bfe_u32 v2, v8, 4, 2
	v_bitop3_b32 v2, v2, v8, 3 bitop3:0x78
	v_cndmask_b32_e32 v1, v1, v4, vcc
	v_xor_b32_e32 v1, v1, v3
	v_sub_u32_e32 v1, v1, v3
	v_ashrrev_i32_e32 v3, 6, v8
	v_readfirstlane_b32 s40, v1
	s_mul_i32 s23, s42, s40
	v_subrev_u32_e32 v0, s23, v0
	s_waitcnt vmcnt(1)
	v_add_u32_e32 v138, s41, v0
	s_ashr_i32 s41, s40, 31
	v_lshlrev_b32_e32 v132, 8, v138
	s_lshl_b64 s[42:43], s[40:41], 19
	v_bfe_u32 v4, v8, 2, 4
	s_mov_b32 s41, 0x1fffc0
	v_ashrrev_i32_e32 v133, 31, v132
	v_lshlrev_b32_e32 v9, 3, v2
	v_and_or_b32 v2, v8, s41, v4
	v_lshlrev_b32_e32 v5, 16, v3
	v_lshlrev_b32_e32 v10, 11, v4
	v_lshlrev_b64 v[130:131], 11, v[132:133]
	v_lshlrev_b64 v[0:1], 12, v[132:133]
	v_lshl_or_b32 v2, v2, 11, v9
	v_or3_b32 v4, v10, v5, v9
	v_lshl_add_u32 v133, v3, 12, 32
	v_lshlrev_b32_e32 v3, 11, v3
	v_lshl_add_u64 v[0:1], s[6:7], 0, v[0:1]
	s_add_u32 s90, s52, s42
	v_sub_u32_e32 v139, v133, v3
	v_ashrrev_i32_e32 v3, 31, v2
	v_ashrrev_i32_e32 v5, 31, v4
	v_readfirstlane_b32 s41, v133
	v_add_u32_e32 v12, 0x400, v133
	s_addc_u32 s91, s53, s43
	v_lshl_add_u64 v[0:1], v[2:3], 1, v[0:1]
	v_lshlrev_b64 v[2:3], 1, v[4:5]
	v_lshrrev_b32_e32 v241, 4, v10
	v_add_u32_e32 v2, v2, v241
	s_mov_b32 m0, s41
	v_readfirstlane_b32 s41, v12
	v_add_u32_e32 v12, 0x800, v133
	v_lshl_add_u64 v[4:5], s[90:91], 0, v[2:3]
	global_load_lds_dwordx4 v[0:1], off
	v_lshl_add_u64 v[6:7], v[0:1], 0, s[10:11]
	s_mov_b32 m0, s41
	s_mov_b64 s[90:91], 0x20000
	v_readfirstlane_b32 s41, v12
	v_add_u32_e32 v12, 0xc00, v133
	v_add_u32_e32 v11, 0x4000, v139
	global_load_lds_dwordx4 v[6:7], off
	v_lshl_add_u64 v[6:7], v[0:1], 0, s[90:91]
	s_mov_b32 m0, s41
	s_mov_b64 s[90:91], 0x30000
	v_readfirstlane_b32 s41, v12
	global_load_lds_dwordx4 v[6:7], off
	v_lshl_add_u64 v[6:7], v[0:1], 0, s[90:91]
	s_mov_b32 m0, s41
	v_readfirstlane_b32 s41, v11
	v_add_u32_e32 v11, 0x4400, v139
	global_load_lds_dwordx4 v[6:7], off
	s_mov_b32 m0, s41
	v_readfirstlane_b32 s41, v11
	v_add_u32_e32 v11, 0x6000, v133
	global_load_lds_dwordx4 v[4:5], off
	s_mov_b64 s[90:91], 0x10800
	v_lshl_add_u64 v[6:7], v[4:5], 0, s[90:91]
	s_mov_b32 m0, s41
	v_readfirstlane_b32 s41, v11
	v_add_u32_e32 v11, 0x6400, v133
	global_load_lds_dwordx4 v[6:7], off
	v_lshl_add_u64 v[6:7], v[0:1], 0, 64
	s_mov_b32 m0, s41
	v_readfirstlane_b32 s41, v11
	v_add_u32_e32 v11, 0x6800, v133
	global_load_lds_dwordx4 v[6:7], off
	v_lshl_add_u64 v[6:7], v[0:1], 0, s[12:13]
	s_mov_b32 m0, s41
	s_mov_b64 s[90:91], 0x20040
	v_readfirstlane_b32 s41, v11
	global_load_lds_dwordx4 v[6:7], off
	v_lshl_add_u64 v[6:7], v[0:1], 0, s[90:91]
	s_mov_b32 m0, s41
	s_mov_b64 s[90:91], 0x30040
	global_load_lds_dwordx4 v[6:7], off
	v_add_u32_e32 v6, 0x6c00, v133
	v_lshl_add_u64 v[0:1], v[0:1], 0, s[90:91]
	v_readfirstlane_b32 s41, v6
	v_add_u32_e32 v6, 0xa000, v139
	s_mov_b32 m0, s41
	v_readfirstlane_b32 s41, v6
	global_load_lds_dwordx4 v[0:1], off
	v_lshl_add_u64 v[0:1], v[4:5], 0, 64
	s_mov_b32 m0, s41
	s_add_u32 s42, s94, s42
	global_load_lds_dwordx4 v[0:1], off
	s_mov_b64 s[90:91], 0x10840
	v_lshl_add_u64 v[0:1], v[4:5], 0, s[90:91]
	v_add_u32_e32 v4, 0xa400, v139
	s_addc_u32 s43, s95, s43
	v_readfirstlane_b32 s41, v4
	s_mov_b32 m0, s41
	v_bfe_u32 v4, v8, 2, 2
	global_load_lds_dwordx4 v[0:1], off
	v_bfe_u32 v0, v8, 5, 1
	v_lshrrev_b32_e32 v1, 2, v8
	v_bitop3_b32 v1, v0, v1, 3 bitop3:0x78
	v_bitop3_b32 v0, v0, v4, 2 bitop3:0x36
	v_lshlrev_b32_e32 v128, 4, v0
	v_subrev_u32_e32 v0, s23, v208
	v_subrev_u32_e32 v0, s33, v0
	v_lshl_add_u64 v[134:135], s[42:43], 0, v[2:3]
	v_lshlrev_b32_e32 v0, 8, v0
	v_lshlrev_b32_e32 v2, 11, v8
	v_lshlrev_b32_e32 v140, 4, v1
	v_ashrrev_i32_e32 v1, 31, v0
	v_and_b32_e32 v2, 0xfffe0000, v2
	v_lshlrev_b64 v[0:1], 12, v[0:1]
	v_or3_b32 v2, v2, v10, v9
	v_ashrrev_i32_e32 v3, 31, v2
	v_lshl_add_u64 v[0:1], s[94:95], 0, v[0:1]
	v_lshlrev_b32_e32 v5, 6, v8
	v_lshl_add_u64 v[136:137], v[2:3], 1, v[0:1]
	v_mov_b32_e32 v0, 0
	v_and_b32_e32 v141, 0xffffe7c0, v5
	s_waitcnt vmcnt(0)
	v_and_b32_e32 v142, 0x17c0, v5
	s_mov_b64 s[42:43], 0
	v_mov_b32_e32 v1, v0
	v_mov_b32_e32 v2, v0
	v_mov_b32_e32 v3, v0
	v_mov_b32_e32 v4, v0
	v_mov_b32_e32 v5, v0
	v_mov_b32_e32 v6, v0
	v_mov_b32_e32 v7, v0
	v_mov_b32_e32 v8, v0
	v_mov_b32_e32 v9, v0
	v_mov_b32_e32 v10, v0
	v_mov_b32_e32 v11, v0
	v_mov_b32_e32 v12, v0
	v_mov_b32_e32 v13, v0
	v_mov_b32_e32 v14, v0
	v_mov_b32_e32 v15, v0
	v_mov_b32_e32 v16, v0
	v_mov_b32_e32 v17, v0
	v_mov_b32_e32 v18, v0
	v_mov_b32_e32 v19, v0
	v_mov_b32_e32 v20, v0
	v_mov_b32_e32 v21, v0
	v_mov_b32_e32 v22, v0
	v_mov_b32_e32 v23, v0
	v_mov_b32_e32 v24, v0
	v_mov_b32_e32 v25, v0
	v_mov_b32_e32 v26, v0
	v_mov_b32_e32 v27, v0
	v_mov_b32_e32 v28, v0
	v_mov_b32_e32 v29, v0
	v_mov_b32_e32 v30, v0
	v_mov_b32_e32 v31, v0
	v_mov_b32_e32 v32, v0
	v_mov_b32_e32 v33, v0
	v_mov_b32_e32 v34, v0
	v_mov_b32_e32 v35, v0
	v_mov_b32_e32 v36, v0
	v_mov_b32_e32 v37, v0
	v_mov_b32_e32 v38, v0
	v_mov_b32_e32 v39, v0
	v_mov_b32_e32 v40, v0
	v_mov_b32_e32 v41, v0
	v_mov_b32_e32 v42, v0
	v_mov_b32_e32 v43, v0
	v_mov_b32_e32 v44, v0
	v_mov_b32_e32 v45, v0
	v_mov_b32_e32 v46, v0
	v_mov_b32_e32 v47, v0
	v_mov_b32_e32 v48, v0
	v_mov_b32_e32 v49, v0
	v_mov_b32_e32 v50, v0
	v_mov_b32_e32 v51, v0
	v_mov_b32_e32 v52, v0
	v_mov_b32_e32 v53, v0
	v_mov_b32_e32 v54, v0
	v_mov_b32_e32 v55, v0
	v_mov_b32_e32 v56, v0
	v_mov_b32_e32 v57, v0
	v_mov_b32_e32 v58, v0
	v_mov_b32_e32 v59, v0
	v_mov_b32_e32 v60, v0
	v_mov_b32_e32 v61, v0
	v_mov_b32_e32 v62, v0
	v_mov_b32_e32 v63, v0
	v_mov_b32_e32 v64, v0
	v_mov_b32_e32 v65, v0
	v_mov_b32_e32 v66, v0
	v_mov_b32_e32 v67, v0
	v_mov_b32_e32 v68, v0
	v_mov_b32_e32 v69, v0
	v_mov_b32_e32 v70, v0
	v_mov_b32_e32 v71, v0
	v_mov_b32_e32 v72, v0
	v_mov_b32_e32 v73, v0
	v_mov_b32_e32 v74, v0
	v_mov_b32_e32 v75, v0
	v_mov_b32_e32 v76, v0
	v_mov_b32_e32 v77, v0
	v_mov_b32_e32 v78, v0
	v_mov_b32_e32 v79, v0
	v_mov_b32_e32 v80, v0
	v_mov_b32_e32 v81, v0
	v_mov_b32_e32 v82, v0
	v_mov_b32_e32 v83, v0
	v_mov_b32_e32 v84, v0
	v_mov_b32_e32 v85, v0
	v_mov_b32_e32 v86, v0
	v_mov_b32_e32 v87, v0
	v_mov_b32_e32 v88, v0
	v_mov_b32_e32 v89, v0
	v_mov_b32_e32 v90, v0
	v_mov_b32_e32 v91, v0
	v_mov_b32_e32 v92, v0
	v_mov_b32_e32 v93, v0
	v_mov_b32_e32 v94, v0
	v_mov_b32_e32 v95, v0
	v_mov_b32_e32 v96, v0
	v_mov_b32_e32 v97, v0
	v_mov_b32_e32 v98, v0
	v_mov_b32_e32 v99, v0
	v_mov_b32_e32 v100, v0
	v_mov_b32_e32 v101, v0
	v_mov_b32_e32 v102, v0
	v_mov_b32_e32 v103, v0
	v_mov_b32_e32 v104, v0
	v_mov_b32_e32 v105, v0
	v_mov_b32_e32 v106, v0
	v_mov_b32_e32 v107, v0
	v_mov_b32_e32 v108, v0
	v_mov_b32_e32 v109, v0
	v_mov_b32_e32 v110, v0
	v_mov_b32_e32 v111, v0
	v_mov_b32_e32 v112, v0
	v_mov_b32_e32 v113, v0
	v_mov_b32_e32 v114, v0
	v_mov_b32_e32 v115, v0
	v_mov_b32_e32 v116, v0
	v_mov_b32_e32 v117, v0
	v_mov_b32_e32 v118, v0
	v_mov_b32_e32 v119, v0
	v_mov_b32_e32 v120, v0
	v_mov_b32_e32 v121, v0
	v_mov_b32_e32 v122, v0
	v_mov_b32_e32 v123, v0
	v_mov_b32_e32 v124, v0
	v_mov_b32_e32 v125, v0
	v_mov_b32_e32 v126, v0
	v_mov_b32_e32 v127, v0
	v_add3_u32 v192, v141, v140, 32
	v_add3_u32 v193, v141, v128, 32
	v_add_u32_e32 v194, 0x4020, v142
	v_add_u32_e32 v195, v194, v128
	v_add_u32_e32 v194, v194, v140
	v_subrev_u32_e32 v196, s94, v136
	v_subrev_u32_e32 v200, s94, v134
	v_add_u32_e32 v196, 0x15c88080, v196
	v_sub_u32_e32 v200, v200, v241
	v_add_u32_e32 v200, 0x18a88000, v200
	v_add_u32_e32 v197, 0x10000, v196
	v_add_u32_e32 v198, 0x20000, v196
	v_add_u32_e32 v199, 0x30000, v196
	v_add_u32_e32 v201, 0x10000, v200
	v_readfirstlane_b32 s22, v133
	v_readfirstlane_b32 s23, v139
	s_mov_b64 s[98:99], s[94:95]
	s_add_u32 s100, s94, 64
	s_addc_u32 s101, s95, 0
	s_add_u32 s23, s23, 0x4000
	v_or_b32_e32 v245, 0x800, v241
	s_movk_i32 s32, 0x80
	s_waitcnt vmcnt(6)
	s_barrier
	ds_read_b128 v[144:147], v194 offset:0
	ds_read_b128 v[148:151], v194 offset:2048
	ds_read_b128 v[152:155], v192 offset:0
	ds_read_b128 v[156:159], v192 offset:2048
	ds_read_b128 v[160:163], v192 offset:4096
	ds_read_b128 v[164:167], v192 offset:6144
	s_waitcnt lgkmcnt(2)
	s_setprio 1
	v_mfma_f32_32x32x16_bf16 v[112:127], v[152:155], v[144:147], v[112:127]
	v_mfma_f32_32x32x16_bf16 v[96:111], v[152:155], v[148:151], v[96:111]
	v_mfma_f32_32x32x16_bf16 v[80:95], v[156:159], v[144:147], v[80:95]
	v_mfma_f32_32x32x16_bf16 v[64:79], v[156:159], v[148:151], v[64:79]
	s_setprio 0
	ds_read_b128 v[168:171], v195 offset:0
	ds_read_b128 v[172:175], v195 offset:2048
	ds_read_b128 v[176:179], v193 offset:0
	ds_read_b128 v[180:183], v193 offset:2048
	s_waitcnt lgkmcnt(4)
	s_setprio 1
	v_mfma_f32_32x32x16_bf16 v[48:63], v[160:163], v[144:147], v[48:63]
	v_mfma_f32_32x32x16_bf16 v[32:47], v[160:163], v[148:151], v[32:47]
	v_mfma_f32_32x32x16_bf16 v[16:31], v[164:167], v[144:147], v[16:31]
	v_mfma_f32_32x32x16_bf16 v[0:15], v[164:167], v[148:151], v[0:15]
	s_setprio 0
	ds_read_b128 v[184:187], v193 offset:4096
	ds_read_b128 v[188:191], v193 offset:6144
	s_waitcnt lgkmcnt(2)
	s_setprio 1
	v_mfma_f32_32x32x16_bf16 v[112:127], v[176:179], v[168:171], v[112:127]
	v_mfma_f32_32x32x16_bf16 v[96:111], v[176:179], v[172:175], v[96:111]
	v_mfma_f32_32x32x16_bf16 v[80:95], v[180:183], v[168:171], v[80:95]
	v_mfma_f32_32x32x16_bf16 v[64:79], v[180:183], v[172:175], v[64:79]
	s_setprio 0
	s_mov_b32 s33, 10
.Lp5m_kloop:
	s_waitcnt vmcnt(0) lgkmcnt(0)
	s_barrier
	ds_read_b128 v[144:147], v194 offset:24576
	ds_read_b128 v[148:151], v194 offset:26624
	ds_read_b128 v[152:155], v192 offset:24576
	ds_read_b128 v[156:159], v192 offset:26624
	ds_read_b128 v[160:163], v192 offset:28672
	ds_read_b128 v[164:167], v192 offset:30720
	s_setprio 1
	v_mfma_f32_32x32x16_bf16 v[48:63], v[184:187], v[168:171], v[48:63]
	v_mfma_f32_32x32x16_bf16 v[32:47], v[184:187], v[172:175], v[32:47]
	v_mfma_f32_32x32x16_bf16 v[16:31], v[188:191], v[168:171], v[16:31]
	v_mfma_f32_32x32x16_bf16 v[0:15], v[188:191], v[172:175], v[0:15]
	s_setprio 0
	s_add_u32 m0, s22, 0xc000
	s_nop 0
	global_load_lds_dwordx4 v196, s[98:99]
	s_add_u32 m0, s22, 0x0
	s_nop 0
	global_load_lds_dwordx4 v196, s[100:101]
	s_add_u32 m0, s22, 0xc400
	s_nop 0
	global_load_lds_dwordx4 v197, s[98:99]
	s_add_u32 m0, s22, 0x400
	s_nop 0
	global_load_lds_dwordx4 v197, s[100:101]
	s_waitcnt lgkmcnt(2)
	s_setprio 1
	v_mfma_f32_32x32x16_bf16 v[112:127], v[152:155], v[144:147], v[112:127]
	v_mfma_f32_32x32x16_bf16 v[96:111], v[152:155], v[148:151], v[96:111]
	v_mfma_f32_32x32x16_bf16 v[80:95], v[156:159], v[144:147], v[80:95]
	v_mfma_f32_32x32x16_bf16 v[64:79], v[156:159], v[148:151], v[64:79]
	s_setprio 0
	ds_read_b128 v[168:171], v195 offset:24576
	ds_read_b128 v[172:175], v195 offset:26624
	ds_read_b128 v[176:179], v193 offset:24576
	ds_read_b128 v[180:183], v193 offset:26624
	s_add_u32 m0, s22, 0xc800
	s_nop 0
	global_load_lds_dwordx4 v198, s[98:99]
	s_add_u32 m0, s22, 0x800
	s_nop 0
	global_load_lds_dwordx4 v198, s[100:101]
	s_add_u32 m0, s22, 0xcc00
	s_nop 0
	global_load_lds_dwordx4 v199, s[98:99]
	s_add_u32 m0, s22, 0xc00
	s_nop 0
	global_load_lds_dwordx4 v199, s[100:101]
	s_waitcnt lgkmcnt(4)
	s_setprio 1
	v_mfma_f32_32x32x16_bf16 v[48:63], v[160:163], v[144:147], v[48:63]
	v_mfma_f32_32x32x16_bf16 v[32:47], v[160:163], v[148:151], v[32:47]
	v_mfma_f32_32x32x16_bf16 v[16:31], v[164:167], v[144:147], v[16:31]
	v_mfma_f32_32x32x16_bf16 v[0:15], v[164:167], v[148:151], v[0:15]
	s_setprio 0
	ds_read_b128 v[184:187], v193 offset:28672
	ds_read_b128 v[188:191], v193 offset:30720
	v_xad_u32 v246, s32, v241, v200
	v_xad_u32 v247, s32, v245, v201
	s_add_u32 m0, s23, 0xc000
	s_nop 0
	global_load_lds_dwordx4 v246, s[94:95]
	s_add_u32 m0, s23, 0xffffffc0
	s_nop 0
	global_load_lds_dwordx4 v246, s[94:95] offset:64
	s_add_u32 m0, s23, 0xc400
	s_nop 0
	global_load_lds_dwordx4 v247, s[94:95]
	s_add_u32 m0, s23, 0x3c0
	s_nop 0
	global_load_lds_dwordx4 v247, s[94:95] offset:64
	s_add_u32 s32, s32, 0x80
	s_add_u32 s98, s98, 128
	s_addc_u32 s99, s99, 0
	s_add_u32 s100, s100, 128
	s_addc_u32 s101, s101, 0
	s_waitcnt lgkmcnt(2)
	s_setprio 1
	v_mfma_f32_32x32x16_bf16 v[112:127], v[176:179], v[168:171], v[112:127]
	v_mfma_f32_32x32x16_bf16 v[96:111], v[176:179], v[172:175], v[96:111]
	v_mfma_f32_32x32x16_bf16 v[80:95], v[180:183], v[168:171], v[80:95]
	v_mfma_f32_32x32x16_bf16 v[64:79], v[180:183], v[172:175], v[64:79]
	s_setprio 0
	s_waitcnt vmcnt(0) lgkmcnt(0)
	s_barrier
	ds_read_b128 v[144:147], v194 offset:49152
	ds_read_b128 v[148:151], v194 offset:51200
	ds_read_b128 v[152:155], v192 offset:49152
	ds_read_b128 v[156:159], v192 offset:51200
	ds_read_b128 v[160:163], v192 offset:53248
	ds_read_b128 v[164:167], v192 offset:55296
	s_setprio 1
	v_mfma_f32_32x32x16_bf16 v[48:63], v[184:187], v[168:171], v[48:63]
	v_mfma_f32_32x32x16_bf16 v[32:47], v[184:187], v[172:175], v[32:47]
	v_mfma_f32_32x32x16_bf16 v[16:31], v[188:191], v[168:171], v[16:31]
	v_mfma_f32_32x32x16_bf16 v[0:15], v[188:191], v[172:175], v[0:15]
	s_setprio 0
	s_waitcnt lgkmcnt(2)
	s_setprio 1
	v_mfma_f32_32x32x16_bf16 v[112:127], v[152:155], v[144:147], v[112:127]
	v_mfma_f32_32x32x16_bf16 v[96:111], v[152:155], v[148:151], v[96:111]
	v_mfma_f32_32x32x16_bf16 v[80:95], v[156:159], v[144:147], v[80:95]
	v_mfma_f32_32x32x16_bf16 v[64:79], v[156:159], v[148:151], v[64:79]
	s_setprio 0
	ds_read_b128 v[168:171], v195 offset:49152
	ds_read_b128 v[172:175], v195 offset:51200
	ds_read_b128 v[176:179], v193 offset:49152
	ds_read_b128 v[180:183], v193 offset:51200
	s_waitcnt lgkmcnt(4)
	s_setprio 1
	v_mfma_f32_32x32x16_bf16 v[48:63], v[160:163], v[144:147], v[48:63]
	v_mfma_f32_32x32x16_bf16 v[32:47], v[160:163], v[148:151], v[32:47]
	v_mfma_f32_32x32x16_bf16 v[16:31], v[164:167], v[144:147], v[16:31]
	v_mfma_f32_32x32x16_bf16 v[0:15], v[164:167], v[148:151], v[0:15]
	s_setprio 0
	ds_read_b128 v[184:187], v193 offset:53248
	ds_read_b128 v[188:191], v193 offset:55296
	s_waitcnt lgkmcnt(2)
	s_setprio 1
	v_mfma_f32_32x32x16_bf16 v[112:127], v[176:179], v[168:171], v[112:127]
	v_mfma_f32_32x32x16_bf16 v[96:111], v[176:179], v[172:175], v[96:111]
	v_mfma_f32_32x32x16_bf16 v[80:95], v[180:183], v[168:171], v[80:95]
	v_mfma_f32_32x32x16_bf16 v[64:79], v[180:183], v[172:175], v[64:79]
	s_setprio 0
	s_waitcnt vmcnt(0) lgkmcnt(0)
	s_barrier
	ds_read_b128 v[144:147], v194 offset:0
	ds_read_b128 v[148:151], v194 offset:2048
	ds_read_b128 v[152:155], v192 offset:0
	ds_read_b128 v[156:159], v192 offset:2048
	ds_read_b128 v[160:163], v192 offset:4096
	ds_read_b128 v[164:167], v192 offset:6144
	s_setprio 1
	v_mfma_f32_32x32x16_bf16 v[48:63], v[184:187], v[168:171], v[48:63]
	v_mfma_f32_32x32x16_bf16 v[32:47], v[184:187], v[172:175], v[32:47]
	v_mfma_f32_32x32x16_bf16 v[16:31], v[188:191], v[168:171], v[16:31]
	v_mfma_f32_32x32x16_bf16 v[0:15], v[188:191], v[172:175], v[0:15]
	s_setprio 0
	s_add_u32 m0, s22, 0x6000
	s_nop 0
	global_load_lds_dwordx4 v196, s[98:99]
	s_add_u32 m0, s22, 0xc000
	s_nop 0
	global_load_lds_dwordx4 v196, s[100:101]
	s_add_u32 m0, s22, 0x6400
	s_nop 0
	global_load_lds_dwordx4 v197, s[98:99]
	s_add_u32 m0, s22, 0xc400
	s_nop 0
	global_load_lds_dwordx4 v197, s[100:101]
	s_waitcnt lgkmcnt(2)
	s_setprio 1
	v_mfma_f32_32x32x16_bf16 v[112:127], v[152:155], v[144:147], v[112:127]
	v_mfma_f32_32x32x16_bf16 v[96:111], v[152:155], v[148:151], v[96:111]
	v_mfma_f32_32x32x16_bf16 v[80:95], v[156:159], v[144:147], v[80:95]
	v_mfma_f32_32x32x16_bf16 v[64:79], v[156:159], v[148:151], v[64:79]
	s_setprio 0
	ds_read_b128 v[168:171], v195 offset:0
	ds_read_b128 v[172:175], v195 offset:2048
	ds_read_b128 v[176:179], v193 offset:0
	ds_read_b128 v[180:183], v193 offset:2048
	s_add_u32 m0, s22, 0x6800
	s_nop 0
	global_load_lds_dwordx4 v198, s[98:99]
	s_add_u32 m0, s22, 0xc800
	s_nop 0
	global_load_lds_dwordx4 v198, s[100:101]
	s_add_u32 m0, s22, 0x6c00
	s_nop 0
	global_load_lds_dwordx4 v199, s[98:99]
	s_add_u32 m0, s22, 0xcc00
	s_nop 0
	global_load_lds_dwordx4 v199, s[100:101]
	s_waitcnt lgkmcnt(4)
	s_setprio 1
	v_mfma_f32_32x32x16_bf16 v[48:63], v[160:163], v[144:147], v[48:63]
	v_mfma_f32_32x32x16_bf16 v[32:47], v[160:163], v[148:151], v[32:47]
	v_mfma_f32_32x32x16_bf16 v[16:31], v[164:167], v[144:147], v[16:31]
	v_mfma_f32_32x32x16_bf16 v[0:15], v[164:167], v[148:151], v[0:15]
	s_setprio 0
	ds_read_b128 v[184:187], v193 offset:4096
	ds_read_b128 v[188:191], v193 offset:6144
	v_xad_u32 v246, s32, v241, v200
	v_xad_u32 v247, s32, v245, v201
	s_add_u32 m0, s23, 0x6000
	s_nop 0
	global_load_lds_dwordx4 v246, s[94:95]
	s_add_u32 m0, s23, 0xbfc0
	s_nop 0
	global_load_lds_dwordx4 v246, s[94:95] offset:64
	s_add_u32 m0, s23, 0x6400
	s_nop 0
	global_load_lds_dwordx4 v247, s[94:95]
	s_add_u32 m0, s23, 0xc3c0
	s_nop 0
	global_load_lds_dwordx4 v247, s[94:95] offset:64
	s_add_u32 s32, s32, 0x80
	s_add_u32 s98, s98, 128
	s_addc_u32 s99, s99, 0
	s_add_u32 s100, s100, 128
	s_addc_u32 s101, s101, 0
	s_waitcnt lgkmcnt(2)
	s_setprio 1
	v_mfma_f32_32x32x16_bf16 v[112:127], v[176:179], v[168:171], v[112:127]
	v_mfma_f32_32x32x16_bf16 v[96:111], v[176:179], v[172:175], v[96:111]
	v_mfma_f32_32x32x16_bf16 v[80:95], v[180:183], v[168:171], v[80:95]
	v_mfma_f32_32x32x16_bf16 v[64:79], v[180:183], v[172:175], v[64:79]
	s_setprio 0
	s_waitcnt vmcnt(0) lgkmcnt(0)
	s_barrier
	ds_read_b128 v[144:147], v194 offset:24576
	ds_read_b128 v[148:151], v194 offset:26624
	ds_read_b128 v[152:155], v192 offset:24576
	ds_read_b128 v[156:159], v192 offset:26624
	ds_read_b128 v[160:163], v192 offset:28672
	ds_read_b128 v[164:167], v192 offset:30720
	s_setprio 1
	v_mfma_f32_32x32x16_bf16 v[48:63], v[184:187], v[168:171], v[48:63]
	v_mfma_f32_32x32x16_bf16 v[32:47], v[184:187], v[172:175], v[32:47]
	v_mfma_f32_32x32x16_bf16 v[16:31], v[188:191], v[168:171], v[16:31]
	v_mfma_f32_32x32x16_bf16 v[0:15], v[188:191], v[172:175], v[0:15]
	s_setprio 0
	s_waitcnt lgkmcnt(2)
	s_setprio 1
	v_mfma_f32_32x32x16_bf16 v[112:127], v[152:155], v[144:147], v[112:127]
	v_mfma_f32_32x32x16_bf16 v[96:111], v[152:155], v[148:151], v[96:111]
	v_mfma_f32_32x32x16_bf16 v[80:95], v[156:159], v[144:147], v[80:95]
	v_mfma_f32_32x32x16_bf16 v[64:79], v[156:159], v[148:151], v[64:79]
	s_setprio 0
	ds_read_b128 v[168:171], v195 offset:24576
	ds_read_b128 v[172:175], v195 offset:26624
	ds_read_b128 v[176:179], v193 offset:24576
	ds_read_b128 v[180:183], v193 offset:26624
	s_waitcnt lgkmcnt(4)
	s_setprio 1
	v_mfma_f32_32x32x16_bf16 v[48:63], v[160:163], v[144:147], v[48:63]
	v_mfma_f32_32x32x16_bf16 v[32:47], v[160:163], v[148:151], v[32:47]
	v_mfma_f32_32x32x16_bf16 v[16:31], v[164:167], v[144:147], v[16:31]
	v_mfma_f32_32x32x16_bf16 v[0:15], v[164:167], v[148:151], v[0:15]
	s_setprio 0
	ds_read_b128 v[184:187], v193 offset:28672
	ds_read_b128 v[188:191], v193 offset:30720
	s_waitcnt lgkmcnt(2)
	s_setprio 1
	v_mfma_f32_32x32x16_bf16 v[112:127], v[176:179], v[168:171], v[112:127]
	v_mfma_f32_32x32x16_bf16 v[96:111], v[176:179], v[172:175], v[96:111]
	v_mfma_f32_32x32x16_bf16 v[80:95], v[180:183], v[168:171], v[80:95]
	v_mfma_f32_32x32x16_bf16 v[64:79], v[180:183], v[172:175], v[64:79]
	s_setprio 0
	s_waitcnt vmcnt(0) lgkmcnt(0)
	s_barrier
	ds_read_b128 v[144:147], v194 offset:49152
	ds_read_b128 v[148:151], v194 offset:51200
	ds_read_b128 v[152:155], v192 offset:49152
	ds_read_b128 v[156:159], v192 offset:51200
	ds_read_b128 v[160:163], v192 offset:53248
	ds_read_b128 v[164:167], v192 offset:55296
	s_setprio 1
	v_mfma_f32_32x32x16_bf16 v[48:63], v[184:187], v[168:171], v[48:63]
	v_mfma_f32_32x32x16_bf16 v[32:47], v[184:187], v[172:175], v[32:47]
	v_mfma_f32_32x32x16_bf16 v[16:31], v[188:191], v[168:171], v[16:31]
	v_mfma_f32_32x32x16_bf16 v[0:15], v[188:191], v[172:175], v[0:15]
	s_setprio 0
	s_add_u32 m0, s22, 0x0
	s_nop 0
	global_load_lds_dwordx4 v196, s[98:99]
	s_add_u32 m0, s22, 0x6000
	s_nop 0
	global_load_lds_dwordx4 v196, s[100:101]
	s_add_u32 m0, s22, 0x400
	s_nop 0
	global_load_lds_dwordx4 v197, s[98:99]
	s_add_u32 m0, s22, 0x6400
	s_nop 0
	global_load_lds_dwordx4 v197, s[100:101]
	s_waitcnt lgkmcnt(2)
	s_setprio 1
	v_mfma_f32_32x32x16_bf16 v[112:127], v[152:155], v[144:147], v[112:127]
	v_mfma_f32_32x32x16_bf16 v[96:111], v[152:155], v[148:151], v[96:111]
	v_mfma_f32_32x32x16_bf16 v[80:95], v[156:159], v[144:147], v[80:95]
	v_mfma_f32_32x32x16_bf16 v[64:79], v[156:159], v[148:151], v[64:79]
	s_setprio 0
	ds_read_b128 v[168:171], v195 offset:49152
	ds_read_b128 v[172:175], v195 offset:51200
	ds_read_b128 v[176:179], v193 offset:49152
	ds_read_b128 v[180:183], v193 offset:51200
	s_add_u32 m0, s22, 0x800
	s_nop 0
	global_load_lds_dwordx4 v198, s[98:99]
	s_add_u32 m0, s22, 0x6800
	s_nop 0
	global_load_lds_dwordx4 v198, s[100:101]
	s_add_u32 m0, s22, 0xc00
	s_nop 0
	global_load_lds_dwordx4 v199, s[98:99]
	s_add_u32 m0, s22, 0x6c00
	s_nop 0
	global_load_lds_dwordx4 v199, s[100:101]
	s_waitcnt lgkmcnt(4)
	s_setprio 1
	v_mfma_f32_32x32x16_bf16 v[48:63], v[160:163], v[144:147], v[48:63]
	v_mfma_f32_32x32x16_bf16 v[32:47], v[160:163], v[148:151], v[32:47]
	v_mfma_f32_32x32x16_bf16 v[16:31], v[164:167], v[144:147], v[16:31]
	v_mfma_f32_32x32x16_bf16 v[0:15], v[164:167], v[148:151], v[0:15]
	s_setprio 0
	ds_read_b128 v[184:187], v193 offset:53248
	ds_read_b128 v[188:191], v193 offset:55296
	v_xad_u32 v246, s32, v241, v200
	v_xad_u32 v247, s32, v245, v201
	s_add_u32 m0, s23, 0x0
	s_nop 0
	global_load_lds_dwordx4 v246, s[94:95]
	s_add_u32 m0, s23, 0x5fc0
	s_nop 0
	global_load_lds_dwordx4 v246, s[94:95] offset:64
	s_add_u32 m0, s23, 0x400
	s_nop 0
	global_load_lds_dwordx4 v247, s[94:95]
	s_add_u32 m0, s23, 0x63c0
	s_nop 0
	global_load_lds_dwordx4 v247, s[94:95] offset:64
	s_add_u32 s32, s32, 0x80
	s_add_u32 s98, s98, 128
	s_addc_u32 s99, s99, 0
	s_add_u32 s100, s100, 128
	s_addc_u32 s101, s101, 0
	s_waitcnt lgkmcnt(2)
	s_setprio 1
	v_mfma_f32_32x32x16_bf16 v[112:127], v[176:179], v[168:171], v[112:127]
	v_mfma_f32_32x32x16_bf16 v[96:111], v[176:179], v[172:175], v[96:111]
	v_mfma_f32_32x32x16_bf16 v[80:95], v[180:183], v[168:171], v[80:95]
	v_mfma_f32_32x32x16_bf16 v[64:79], v[180:183], v[172:175], v[64:79]
	s_setprio 0
	s_waitcnt vmcnt(0) lgkmcnt(0)
	s_barrier
	ds_read_b128 v[144:147], v194 offset:0
	ds_read_b128 v[148:151], v194 offset:2048
	ds_read_b128 v[152:155], v192 offset:0
	ds_read_b128 v[156:159], v192 offset:2048
	ds_read_b128 v[160:163], v192 offset:4096
	ds_read_b128 v[164:167], v192 offset:6144
	s_setprio 1
	v_mfma_f32_32x32x16_bf16 v[48:63], v[184:187], v[168:171], v[48:63]
	v_mfma_f32_32x32x16_bf16 v[32:47], v[184:187], v[172:175], v[32:47]
	v_mfma_f32_32x32x16_bf16 v[16:31], v[188:191], v[168:171], v[16:31]
	v_mfma_f32_32x32x16_bf16 v[0:15], v[188:191], v[172:175], v[0:15]
	s_setprio 0
	s_waitcnt lgkmcnt(2)
	s_setprio 1
	v_mfma_f32_32x32x16_bf16 v[112:127], v[152:155], v[144:147], v[112:127]
	v_mfma_f32_32x32x16_bf16 v[96:111], v[152:155], v[148:151], v[96:111]
	v_mfma_f32_32x32x16_bf16 v[80:95], v[156:159], v[144:147], v[80:95]
	v_mfma_f32_32x32x16_bf16 v[64:79], v[156:159], v[148:151], v[64:79]
	s_setprio 0
	ds_read_b128 v[168:171], v195 offset:0
	ds_read_b128 v[172:175], v195 offset:2048
	ds_read_b128 v[176:179], v193 offset:0
	ds_read_b128 v[180:183], v193 offset:2048
	s_waitcnt lgkmcnt(4)
	s_setprio 1
	v_mfma_f32_32x32x16_bf16 v[48:63], v[160:163], v[144:147], v[48:63]
	v_mfma_f32_32x32x16_bf16 v[32:47], v[160:163], v[148:151], v[32:47]
	v_mfma_f32_32x32x16_bf16 v[16:31], v[164:167], v[144:147], v[16:31]
	v_mfma_f32_32x32x16_bf16 v[0:15], v[164:167], v[148:151], v[0:15]
	s_setprio 0
	ds_read_b128 v[184:187], v193 offset:4096
	ds_read_b128 v[188:191], v193 offset:6144
	s_waitcnt lgkmcnt(2)
	s_setprio 1
	v_mfma_f32_32x32x16_bf16 v[112:127], v[176:179], v[168:171], v[112:127]
	v_mfma_f32_32x32x16_bf16 v[96:111], v[176:179], v[172:175], v[96:111]
	v_mfma_f32_32x32x16_bf16 v[80:95], v[180:183], v[168:171], v[80:95]
	v_mfma_f32_32x32x16_bf16 v[64:79], v[180:183], v[172:175], v[64:79]
	s_setprio 0
	s_sub_u32 s33, s33, 1
	s_cmp_lg_u32 s33, 0
	s_cbranch_scc1 .Lp5m_kloop
	s_waitcnt vmcnt(0) lgkmcnt(0)
	s_barrier
	ds_read_b128 v[144:147], v194 offset:24576
	ds_read_b128 v[148:151], v194 offset:26624
	ds_read_b128 v[152:155], v192 offset:24576
	ds_read_b128 v[156:159], v192 offset:26624
	ds_read_b128 v[160:163], v192 offset:28672
	ds_read_b128 v[164:167], v192 offset:30720
	s_setprio 1
	v_mfma_f32_32x32x16_bf16 v[48:63], v[184:187], v[168:171], v[48:63]
	v_mfma_f32_32x32x16_bf16 v[32:47], v[184:187], v[172:175], v[32:47]
	v_mfma_f32_32x32x16_bf16 v[16:31], v[188:191], v[168:171], v[16:31]
	v_mfma_f32_32x32x16_bf16 v[0:15], v[188:191], v[172:175], v[0:15]
	s_setprio 0
	s_add_u32 m0, s22, 0xc000
	s_nop 0
	global_load_lds_dwordx4 v196, s[98:99]
	s_add_u32 m0, s22, 0x0
	s_nop 0
	global_load_lds_dwordx4 v196, s[100:101]
	s_add_u32 m0, s22, 0xc400
	s_nop 0
	global_load_lds_dwordx4 v197, s[98:99]
	s_add_u32 m0, s22, 0x400
	s_nop 0
	global_load_lds_dwordx4 v197, s[100:101]
	s_waitcnt lgkmcnt(2)
	s_setprio 1
	v_mfma_f32_32x32x16_bf16 v[112:127], v[152:155], v[144:147], v[112:127]
	v_mfma_f32_32x32x16_bf16 v[96:111], v[152:155], v[148:151], v[96:111]
	v_mfma_f32_32x32x16_bf16 v[80:95], v[156:159], v[144:147], v[80:95]
	v_mfma_f32_32x32x16_bf16 v[64:79], v[156:159], v[148:151], v[64:79]
	s_setprio 0
	ds_read_b128 v[168:171], v195 offset:24576
	ds_read_b128 v[172:175], v195 offset:26624
	ds_read_b128 v[176:179], v193 offset:24576
	ds_read_b128 v[180:183], v193 offset:26624
	s_add_u32 m0, s22, 0xc800
	s_nop 0
	global_load_lds_dwordx4 v198, s[98:99]
	s_add_u32 m0, s22, 0x800
	s_nop 0
	global_load_lds_dwordx4 v198, s[100:101]
	s_add_u32 m0, s22, 0xcc00
	s_nop 0
	global_load_lds_dwordx4 v199, s[98:99]
	s_add_u32 m0, s22, 0xc00
	s_nop 0
	global_load_lds_dwordx4 v199, s[100:101]
	s_waitcnt lgkmcnt(4)
	s_setprio 1
	v_mfma_f32_32x32x16_bf16 v[48:63], v[160:163], v[144:147], v[48:63]
	v_mfma_f32_32x32x16_bf16 v[32:47], v[160:163], v[148:151], v[32:47]
	v_mfma_f32_32x32x16_bf16 v[16:31], v[164:167], v[144:147], v[16:31]
	v_mfma_f32_32x32x16_bf16 v[0:15], v[164:167], v[148:151], v[0:15]
	s_setprio 0
	ds_read_b128 v[184:187], v193 offset:28672
	ds_read_b128 v[188:191], v193 offset:30720
	v_xad_u32 v246, s32, v241, v200
	v_xad_u32 v247, s32, v245, v201
	s_add_u32 m0, s23, 0xc000
	s_nop 0
	global_load_lds_dwordx4 v246, s[94:95]
	s_add_u32 m0, s23, 0xffffffc0
	s_nop 0
	global_load_lds_dwordx4 v246, s[94:95] offset:64
	s_add_u32 m0, s23, 0xc400
	s_nop 0
	global_load_lds_dwordx4 v247, s[94:95]
	s_add_u32 m0, s23, 0x3c0
	s_nop 0
	global_load_lds_dwordx4 v247, s[94:95] offset:64
	s_add_u32 s32, s32, 0x80
	s_add_u32 s98, s98, 128
	s_addc_u32 s99, s99, 0
	s_add_u32 s100, s100, 128
	s_addc_u32 s101, s101, 0
	s_waitcnt lgkmcnt(2)
	s_setprio 1
	v_mfma_f32_32x32x16_bf16 v[112:127], v[176:179], v[168:171], v[112:127]
	v_mfma_f32_32x32x16_bf16 v[96:111], v[176:179], v[172:175], v[96:111]
	v_mfma_f32_32x32x16_bf16 v[80:95], v[180:183], v[168:171], v[80:95]
	v_mfma_f32_32x32x16_bf16 v[64:79], v[180:183], v[172:175], v[64:79]
	s_setprio 0
	s_waitcnt vmcnt(0) lgkmcnt(0)
	s_barrier
	ds_read_b128 v[144:147], v194 offset:49152
	ds_read_b128 v[148:151], v194 offset:51200
	ds_read_b128 v[152:155], v192 offset:49152
	ds_read_b128 v[156:159], v192 offset:51200
	ds_read_b128 v[160:163], v192 offset:53248
	ds_read_b128 v[164:167], v192 offset:55296
	s_setprio 1
	v_mfma_f32_32x32x16_bf16 v[48:63], v[184:187], v[168:171], v[48:63]
	v_mfma_f32_32x32x16_bf16 v[32:47], v[184:187], v[172:175], v[32:47]
	v_mfma_f32_32x32x16_bf16 v[16:31], v[188:191], v[168:171], v[16:31]
	v_mfma_f32_32x32x16_bf16 v[0:15], v[188:191], v[172:175], v[0:15]
	s_setprio 0
	s_waitcnt lgkmcnt(2)
	s_setprio 1
	v_mfma_f32_32x32x16_bf16 v[112:127], v[152:155], v[144:147], v[112:127]
	v_mfma_f32_32x32x16_bf16 v[96:111], v[152:155], v[148:151], v[96:111]
	v_mfma_f32_32x32x16_bf16 v[80:95], v[156:159], v[144:147], v[80:95]
	v_mfma_f32_32x32x16_bf16 v[64:79], v[156:159], v[148:151], v[64:79]
	s_setprio 0
	ds_read_b128 v[168:171], v195 offset:49152
	ds_read_b128 v[172:175], v195 offset:51200
	ds_read_b128 v[176:179], v193 offset:49152
	ds_read_b128 v[180:183], v193 offset:51200
	s_waitcnt lgkmcnt(4)
	s_setprio 1
	v_mfma_f32_32x32x16_bf16 v[48:63], v[160:163], v[144:147], v[48:63]
	v_mfma_f32_32x32x16_bf16 v[32:47], v[160:163], v[148:151], v[32:47]
	v_mfma_f32_32x32x16_bf16 v[16:31], v[164:167], v[144:147], v[16:31]
	v_mfma_f32_32x32x16_bf16 v[0:15], v[164:167], v[148:151], v[0:15]
	s_setprio 0
	ds_read_b128 v[184:187], v193 offset:53248
	ds_read_b128 v[188:191], v193 offset:55296
	s_waitcnt lgkmcnt(2)
	s_setprio 1
	v_mfma_f32_32x32x16_bf16 v[112:127], v[176:179], v[168:171], v[112:127]
	v_mfma_f32_32x32x16_bf16 v[96:111], v[176:179], v[172:175], v[96:111]
	v_mfma_f32_32x32x16_bf16 v[80:95], v[180:183], v[168:171], v[80:95]
	v_mfma_f32_32x32x16_bf16 v[64:79], v[180:183], v[172:175], v[64:79]
	s_setprio 0
	s_waitcnt vmcnt(0) lgkmcnt(0)
	s_barrier
	ds_read_b128 v[144:147], v194 offset:0
	ds_read_b128 v[148:151], v194 offset:2048
	ds_read_b128 v[152:155], v192 offset:0
	ds_read_b128 v[156:159], v192 offset:2048
	ds_read_b128 v[160:163], v192 offset:4096
	ds_read_b128 v[164:167], v192 offset:6144
	s_setprio 1
	v_mfma_f32_32x32x16_bf16 v[48:63], v[184:187], v[168:171], v[48:63]
	v_mfma_f32_32x32x16_bf16 v[32:47], v[184:187], v[172:175], v[32:47]
	v_mfma_f32_32x32x16_bf16 v[16:31], v[188:191], v[168:171], v[16:31]
	v_mfma_f32_32x32x16_bf16 v[0:15], v[188:191], v[172:175], v[0:15]
	s_setprio 0
	s_waitcnt lgkmcnt(2)
	s_setprio 1
	v_mfma_f32_32x32x16_bf16 v[112:127], v[152:155], v[144:147], v[112:127]
	v_mfma_f32_32x32x16_bf16 v[96:111], v[152:155], v[148:151], v[96:111]
	v_mfma_f32_32x32x16_bf16 v[80:95], v[156:159], v[144:147], v[80:95]
	v_mfma_f32_32x32x16_bf16 v[64:79], v[156:159], v[148:151], v[64:79]
	s_setprio 0
	ds_read_b128 v[168:171], v195 offset:0
	ds_read_b128 v[172:175], v195 offset:2048
	ds_read_b128 v[176:179], v193 offset:0
	ds_read_b128 v[180:183], v193 offset:2048
	s_waitcnt lgkmcnt(4)
	s_setprio 1
	v_mfma_f32_32x32x16_bf16 v[48:63], v[160:163], v[144:147], v[48:63]
	v_mfma_f32_32x32x16_bf16 v[32:47], v[160:163], v[148:151], v[32:47]
	v_mfma_f32_32x32x16_bf16 v[16:31], v[164:167], v[144:147], v[16:31]
	v_mfma_f32_32x32x16_bf16 v[0:15], v[164:167], v[148:151], v[0:15]
	s_setprio 0
	ds_read_b128 v[184:187], v193 offset:4096
	ds_read_b128 v[188:191], v193 offset:6144
	s_waitcnt lgkmcnt(2)
	s_setprio 1
	v_mfma_f32_32x32x16_bf16 v[112:127], v[176:179], v[168:171], v[112:127]
	v_mfma_f32_32x32x16_bf16 v[96:111], v[176:179], v[172:175], v[96:111]
	v_mfma_f32_32x32x16_bf16 v[80:95], v[180:183], v[168:171], v[80:95]
	v_mfma_f32_32x32x16_bf16 v[64:79], v[180:183], v[172:175], v[64:79]
	s_setprio 0
	s_waitcnt lgkmcnt(0)
	s_setprio 1
	v_mfma_f32_32x32x16_bf16 v[48:63], v[184:187], v[168:171], v[48:63]
	v_mfma_f32_32x32x16_bf16 v[32:47], v[184:187], v[172:175], v[32:47]
	v_mfma_f32_32x32x16_bf16 v[16:31], v[188:191], v[168:171], v[16:31]
	v_mfma_f32_32x32x16_bf16 v[0:15], v[188:191], v[172:175], v[0:15]
	s_setprio 0
	s_load_dwordx16 s[60:75], s[0:1], 0x0
	v_add_u32_e32 v128, 0xffffe000, v132
	v_lshlrev_b64 v[134:135], 2, v[130:131]
	v_lshlrev_b64 v[132:133], 13, v[128:129]
	v_cmp_gt_i32_e32 vcc, 32, v138
	s_waitcnt lgkmcnt(0)
	v_lshl_add_u64 v[136:137], s[60:61], 0, v[134:135]
	v_lshl_add_u64 v[132:133], s[62:63], 0, v[132:133]
	v_lshlrev_b64 v[130:131], 1, v[130:131]
	v_cndmask_b32_e32 v133, v133, v137, vcc
	v_cndmask_b32_e32 v132, v132, v136, vcc
	v_lshl_add_u64 v[136:137], s[8:9], 0, v[130:131]
	v_mov_b32_e32 v130, v204
	s_waitcnt vmcnt(0)
	s_barrier
	s_load_dwordx16 s[60:75], s[0:1], 0xc0
	s_lshl_b32 s40, s40, 7
	v_and_b32_e32 v131, 0x1fff80, v130
	v_and_b32_e32 v138, 0x5f, v130
	v_lshrrev_b32_e32 v130, 3, v130
	v_and_or_b32 v130, v130, 4, v131
	s_ashr_i32 s41, s40, 31
	v_lshl_or_b32 v130, v130, 11, v138
	s_lshl_b64 s[42:43], s[40:41], 2
	v_ashrrev_i32_e32 v131, 31, v130
	v_lshl_add_u64 v[132:133], v[132:133], 0, s[42:43]
	s_waitcnt lgkmcnt(0)
	s_add_u32 s22, s66, s42
	v_lshlrev_b64 v[140:141], 2, v[130:131]
	s_addc_u32 s23, s67, s43
	v_lshlrev_b32_e32 v128, 2, v138
	v_lshl_add_u64 v[138:139], v[132:133], 0, v[140:141]
	v_or_b32_e32 v188, 0x800, v130
	global_load_dword v209, v128, s[22:23]
	s_nop 0
	global_load_dword v128, v128, s[22:23] offset:128
	v_ashrrev_i32_e32 v189, 31, v188
	global_load_dword v142, v[138:139], off
	v_lshlrev_b64 v[202:203], 2, v[188:189]
	v_lshl_add_u64 v[144:145], v[132:133], 0, v[202:203]
	v_or_b32_e32 v184, 0x1000, v130
	global_load_dword v240, v[144:145], off
	v_ashrrev_i32_e32 v185, 31, v184
	v_lshlrev_b64 v[200:201], 2, v[184:185]
	v_lshl_add_u64 v[144:145], v[132:133], 0, v[200:201]
	v_or_b32_e32 v178, 0x1800, v130
	global_load_dword v239, v[144:145], off
	v_ashrrev_i32_e32 v179, 31, v178
	v_lshlrev_b64 v[198:199], 2, v[178:179]
	v_lshl_add_u64 v[144:145], v[132:133], 0, v[198:199]
	v_or_b32_e32 v174, 0x4000, v130
	global_load_dword v238, v[144:145], off
	v_ashrrev_i32_e32 v175, 31, v174
	v_lshlrev_b64 v[196:197], 2, v[174:175]
	v_lshl_add_u64 v[144:145], v[132:133], 0, v[196:197]
	v_or_b32_e32 v170, 0x4800, v130
	global_load_dword v237, v[144:145], off
	v_ashrrev_i32_e32 v171, 31, v170
	v_lshlrev_b64 v[194:195], 2, v[170:171]
	v_lshl_add_u64 v[144:145], v[132:133], 0, v[194:195]
	v_or_b32_e32 v166, 0x5000, v130
	global_load_dword v236, v[144:145], off
	v_ashrrev_i32_e32 v167, 31, v166
	v_lshlrev_b64 v[192:193], 2, v[166:167]
	v_lshl_add_u64 v[144:145], v[132:133], 0, v[192:193]
	v_or_b32_e32 v162, 0x5800, v130
	global_load_dword v235, v[144:145], off
	v_ashrrev_i32_e32 v163, 31, v162
	v_lshlrev_b64 v[190:191], 2, v[162:163]
	v_lshl_add_u64 v[144:145], v[132:133], 0, v[190:191]
	v_or_b32_e32 v158, 0x8000, v130
	global_load_dword v233, v[144:145], off
	v_ashrrev_i32_e32 v159, 31, v158
	v_lshlrev_b64 v[186:187], 2, v[158:159]
	v_lshl_add_u64 v[144:145], v[132:133], 0, v[186:187]
	v_or_b32_e32 v154, 0x8800, v130
	global_load_dword v232, v[144:145], off
	v_ashrrev_i32_e32 v155, 31, v154
	v_lshlrev_b64 v[180:181], 2, v[154:155]
	v_lshl_add_u64 v[144:145], v[132:133], 0, v[180:181]
	v_or_b32_e32 v152, 0x9000, v130
	global_load_dword v230, v[144:145], off
	v_ashrrev_i32_e32 v153, 31, v152
	v_lshlrev_b64 v[176:177], 2, v[152:153]
	v_lshl_add_u64 v[144:145], v[132:133], 0, v[176:177]
	v_or_b32_e32 v150, 0x9800, v130
	global_load_dword v229, v[144:145], off
	v_ashrrev_i32_e32 v151, 31, v150
	v_lshlrev_b64 v[172:173], 2, v[150:151]
	v_lshl_add_u64 v[144:145], v[132:133], 0, v[172:173]
	v_or_b32_e32 v148, 0xc000, v130
	global_load_dword v228, v[144:145], off
	v_ashrrev_i32_e32 v149, 31, v148
	v_or_b32_e32 v146, 0xc800, v130
	v_lshlrev_b64 v[168:169], 2, v[148:149]
	v_ashrrev_i32_e32 v147, 31, v146
	v_lshl_add_u64 v[144:145], v[132:133], 0, v[168:169]
	v_lshlrev_b64 v[164:165], 2, v[146:147]
	global_load_dword v227, v[144:145], off
	v_lshl_add_u64 v[144:145], v[132:133], 0, v[164:165]
	global_load_dword v226, v[144:145], off
	v_or_b32_e32 v144, 0xd000, v130
	v_ashrrev_i32_e32 v145, 31, v144
	v_lshlrev_b64 v[160:161], 2, v[144:145]
	v_lshl_add_u64 v[156:157], v[132:133], 0, v[160:161]
	global_load_dword v234, v[156:157], off
	v_or_b32_e32 v156, 0xd800, v130
	v_ashrrev_i32_e32 v157, 31, v156
	v_lshlrev_b64 v[182:183], 2, v[156:157]
	v_lshl_add_u64 v[210:211], v[132:133], 0, v[182:183]
	global_load_dword v231, v[210:211], off
	s_lshl_b64 s[22:23], s[40:41], 1
	v_lshl_add_u64 v[136:137], v[136:137], 0, s[22:23]
	s_movk_i32 s22, 0x2000
	v_add_co_u32_e32 v212, vcc, s22, v138
	s_movk_i32 s22, 0x4000
	s_nop 0
	v_addc_co_u32_e32 v213, vcc, 0, v139, vcc
	global_load_dword v210, v[138:139], off offset:128
	global_load_dword v211, v[212:213], off offset:128
	v_add_co_u32_e32 v212, vcc, s22, v138
	s_movk_i32 s22, 0x6000
	s_nop 0
	v_addc_co_u32_e32 v213, vcc, 0, v139, vcc
	v_add_co_u32_e32 v214, vcc, s22, v138
	s_mov_b32 s22, 0x10000
	s_nop 0
	v_addc_co_u32_e32 v215, vcc, 0, v139, vcc
	global_load_dword v212, v[212:213], off offset:128
	v_lshl_add_u64 v[134:135], s[92:93], 0, v[134:135]
	global_load_dword v213, v[214:215], off offset:128
	v_add_co_u32_e32 v214, vcc, s22, v138
	s_mov_b32 s22, 0x12000
	s_nop 0
	v_addc_co_u32_e32 v215, vcc, 0, v139, vcc
	v_add_co_u32_e32 v216, vcc, s22, v138
	s_mov_b32 s22, 0x14000
	s_nop 0
	v_addc_co_u32_e32 v217, vcc, 0, v139, vcc
	global_load_dword v214, v[214:215], off offset:128
	v_lshl_add_u64 v[134:135], v[134:135], 0, s[42:43]
	global_load_dword v215, v[216:217], off offset:128
	v_add_co_u32_e32 v216, vcc, s22, v138
	s_mov_b32 s22, 0x16000
	s_nop 0
	v_addc_co_u32_e32 v217, vcc, 0, v139, vcc
	v_add_co_u32_e32 v218, vcc, s22, v138
	s_mov_b32 s22, 0x20000
	s_nop 0
	v_addc_co_u32_e32 v219, vcc, 0, v139, vcc
	global_load_dword v216, v[216:217], off offset:128
	s_waitcnt vmcnt(22)
	v_add_f32_e32 v112, v112, v142
	global_load_dword v220, v[218:219], off offset:128
	v_add_co_u32_e32 v218, vcc, s22, v138
	s_mov_b32 s22, 0x22000
	s_nop 0
	v_addc_co_u32_e32 v219, vcc, 0, v139, vcc
	global_load_dword v221, v[218:219], off offset:128
	v_add_co_u32_e32 v218, vcc, s22, v138
	s_mov_b32 s22, 0x24000
	s_nop 0
	v_addc_co_u32_e32 v219, vcc, 0, v139, vcc
	global_load_dword v223, v[218:219], off offset:128
	v_add_co_u32_e32 v218, vcc, s22, v138
	s_mov_b32 s22, 0x26000
	s_nop 0
	v_addc_co_u32_e32 v219, vcc, 0, v139, vcc
	global_load_dword v224, v[218:219], off offset:128
	v_add_co_u32_e32 v218, vcc, s22, v138
	s_mov_b32 s22, 0x30000
	s_nop 0
	v_addc_co_u32_e32 v219, vcc, 0, v139, vcc
	global_load_dword v225, v[218:219], off offset:128
	v_add_co_u32_e32 v218, vcc, s22, v138
	s_mov_b32 s22, 0x32000
	s_nop 0
	v_addc_co_u32_e32 v219, vcc, 0, v139, vcc
	global_load_dword v222, v[218:219], off offset:128
	v_add_co_u32_e32 v218, vcc, s22, v138
	s_mov_b32 s22, 0x34000
	s_nop 0
	v_addc_co_u32_e32 v219, vcc, 0, v139, vcc
	v_add_co_u32_e32 v242, vcc, s22, v138
	s_mov_b32 s22, 0x36000
	s_nop 0
	v_addc_co_u32_e32 v243, vcc, 0, v139, vcc
	global_load_dword v218, v[218:219], off offset:128
	v_lshl_add_u64 v[140:141], v[134:135], 0, v[140:141]
	global_load_dword v217, v[242:243], off offset:128
	v_add_co_u32_e32 v242, vcc, s22, v138
	v_lshl_add_u64 v[142:143], v[130:131], 1, v[136:137]
	s_nop 0
	v_addc_co_u32_e32 v243, vcc, 0, v139, vcc
	global_load_dword v219, v[242:243], off offset:128
	s_waitcnt vmcnt(30)
	v_add_f32_e32 v131, v113, v240
	global_store_dword v[140:141], v112, off
	v_mul_f32_e32 v112, v209, v112
	v_cvt_pk_bf16_f32 v112, v112, s0
	global_store_short v[142:143], v112, off
	v_lshl_add_u64 v[112:113], v[134:135], 0, v[202:203]
	global_store_dword v[112:113], v131, off
	v_mul_f32_e32 v112, v209, v131
	v_cvt_pk_bf16_f32 v131, v112, s0
	v_lshl_add_u64 v[112:113], v[188:189], 1, v[136:137]
	global_store_short v[112:113], v131, off
	s_waitcnt vmcnt(33)
	v_add_f32_e32 v114, v114, v239
	v_lshl_add_u64 v[112:113], v[134:135], 0, v[200:201]
	global_store_dword v[112:113], v114, off
	v_mul_f32_e32 v112, v209, v114
	v_cvt_pk_bf16_f32 v114, v112, s0
	v_lshl_add_u64 v[112:113], v[184:185], 1, v[136:137]
	global_store_short v[112:113], v114, off
	s_waitcnt vmcnt(34)
	v_add_f32_e32 v114, v115, v238
	v_lshl_add_u64 v[112:113], v[134:135], 0, v[198:199]
	global_store_dword v[112:113], v114, off
	v_mul_f32_e32 v112, v209, v114
	v_cvt_pk_bf16_f32 v114, v112, s0
	v_lshl_add_u64 v[112:113], v[178:179], 1, v[136:137]
	global_store_short v[112:113], v114, off
	s_waitcnt vmcnt(35)
	v_add_f32_e32 v114, v116, v237
	v_lshl_add_u64 v[112:113], v[134:135], 0, v[196:197]
	global_store_dword v[112:113], v114, off
	v_mul_f32_e32 v112, v209, v114
	v_cvt_pk_bf16_f32 v114, v112, s0
	v_lshl_add_u64 v[112:113], v[174:175], 1, v[136:137]
	global_store_short v[112:113], v114, off
	s_waitcnt vmcnt(36)
	v_add_f32_e32 v114, v117, v236
	v_lshl_add_u64 v[112:113], v[134:135], 0, v[194:195]
	global_store_dword v[112:113], v114, off
	v_mul_f32_e32 v112, v209, v114
	v_cvt_pk_bf16_f32 v114, v112, s0
	v_lshl_add_u64 v[112:113], v[170:171], 1, v[136:137]
	global_store_short v[112:113], v114, off
	s_waitcnt vmcnt(37)
	v_add_f32_e32 v114, v118, v235
	v_lshl_add_u64 v[112:113], v[134:135], 0, v[192:193]
	global_store_dword v[112:113], v114, off
	v_mul_f32_e32 v112, v209, v114
	v_cvt_pk_bf16_f32 v114, v112, s0
	v_lshl_add_u64 v[112:113], v[166:167], 1, v[136:137]
	global_store_short v[112:113], v114, off
	s_waitcnt vmcnt(38)
	v_add_f32_e32 v114, v119, v233
	v_lshl_add_u64 v[112:113], v[134:135], 0, v[190:191]
	global_store_dword v[112:113], v114, off
	v_mul_f32_e32 v112, v209, v114
	v_cvt_pk_bf16_f32 v114, v112, s0
	v_lshl_add_u64 v[112:113], v[162:163], 1, v[136:137]
	global_store_short v[112:113], v114, off
	s_waitcnt vmcnt(39)
	v_add_f32_e32 v114, v120, v232
	v_lshl_add_u64 v[112:113], v[134:135], 0, v[186:187]
	global_store_dword v[112:113], v114, off
	v_mul_f32_e32 v112, v209, v114
	v_cvt_pk_bf16_f32 v114, v112, s0
	v_lshl_add_u64 v[112:113], v[158:159], 1, v[136:137]
	global_store_short v[112:113], v114, off
	s_waitcnt vmcnt(40)
	v_add_f32_e32 v114, v121, v230
	v_lshl_add_u64 v[112:113], v[134:135], 0, v[180:181]
	global_store_dword v[112:113], v114, off
	v_mul_f32_e32 v112, v209, v114
	v_cvt_pk_bf16_f32 v114, v112, s0
	v_lshl_add_u64 v[112:113], v[154:155], 1, v[136:137]
	global_store_short v[112:113], v114, off
	s_waitcnt vmcnt(41)
	v_add_f32_e32 v114, v122, v229
	v_lshl_add_u64 v[112:113], v[134:135], 0, v[176:177]
	global_store_dword v[112:113], v114, off
	v_mul_f32_e32 v112, v209, v114
	v_cvt_pk_bf16_f32 v114, v112, s0
	v_lshl_add_u64 v[112:113], v[152:153], 1, v[136:137]
	global_store_short v[112:113], v114, off
	s_waitcnt vmcnt(42)
	v_add_f32_e32 v114, v123, v228
	v_lshl_add_u64 v[112:113], v[134:135], 0, v[172:173]
	global_store_dword v[112:113], v114, off
	v_mul_f32_e32 v112, v209, v114
	v_cvt_pk_bf16_f32 v114, v112, s0
	v_lshl_add_u64 v[112:113], v[150:151], 1, v[136:137]
	global_store_short v[112:113], v114, off
	s_waitcnt vmcnt(43)
	v_add_f32_e32 v114, v124, v227
	v_lshl_add_u64 v[112:113], v[134:135], 0, v[168:169]
	global_store_dword v[112:113], v114, off
	v_mul_f32_e32 v112, v209, v114
	v_cvt_pk_bf16_f32 v114, v112, s0
	v_lshl_add_u64 v[112:113], v[148:149], 1, v[136:137]
	global_store_short v[112:113], v114, off
	s_waitcnt vmcnt(44)
	v_add_f32_e32 v114, v125, v226
	v_lshl_add_u64 v[112:113], v[134:135], 0, v[164:165]
	global_store_dword v[112:113], v114, off
	v_mul_f32_e32 v112, v209, v114
	v_cvt_pk_bf16_f32 v114, v112, s0
	v_lshl_add_u64 v[112:113], v[146:147], 1, v[136:137]
	global_store_short v[112:113], v114, off
	s_waitcnt vmcnt(45)
	v_add_f32_e32 v114, v126, v234
	v_lshl_add_u64 v[112:113], v[134:135], 0, v[160:161]
	global_store_dword v[112:113], v114, off
	v_mul_f32_e32 v112, v209, v114
	v_cvt_pk_bf16_f32 v114, v112, s0
	v_lshl_add_u64 v[112:113], v[144:145], 1, v[136:137]
	global_store_short v[112:113], v114, off
	s_waitcnt vmcnt(46)
	v_add_f32_e32 v114, v127, v231
	v_lshl_add_u64 v[112:113], v[134:135], 0, v[182:183]
	global_store_dword v[112:113], v114, off
	v_mul_f32_e32 v112, v209, v114
	v_cvt_pk_bf16_f32 v114, v112, s0
	v_lshl_add_u64 v[112:113], v[156:157], 1, v[136:137]
	s_mov_b32 s22, 0x40000
	global_store_short v[112:113], v114, off
	v_add_co_u32_e32 v112, vcc, s22, v138
	s_mov_b32 s22, 0x42000
	s_nop 0
	v_addc_co_u32_e32 v113, vcc, 0, v139, vcc
	global_load_dword v148, v[112:113], off
	v_add_co_u32_e32 v112, vcc, s22, v138
	s_mov_b32 s22, 0x44000
	s_nop 0
	v_addc_co_u32_e32 v113, vcc, 0, v139, vcc
	v_add_co_u32_e32 v114, vcc, s22, v138
	s_mov_b32 s22, 0x46000
	s_nop 0
	v_addc_co_u32_e32 v115, vcc, 0, v139, vcc
	v_add_co_u32_e32 v116, vcc, s22, v138
	s_mov_b32 s22, 0x50000
	s_nop 0
	v_addc_co_u32_e32 v117, vcc, 0, v139, vcc
	v_add_co_u32_e32 v118, vcc, s22, v138
	s_mov_b32 s22, 0x52000
	s_nop 0
	v_addc_co_u32_e32 v119, vcc, 0, v139, vcc
	v_add_co_u32_e32 v120, vcc, s22, v138
	s_mov_b32 s22, 0x54000
	s_nop 0
	v_addc_co_u32_e32 v121, vcc, 0, v139, vcc
	v_add_co_u32_e32 v122, vcc, s22, v138
	s_mov_b32 s22, 0x56000
	s_nop 0
	v_addc_co_u32_e32 v123, vcc, 0, v139, vcc
	v_add_co_u32_e32 v124, vcc, s22, v138
	s_mov_b32 s22, 0x60000
	s_nop 0
	v_addc_co_u32_e32 v125, vcc, 0, v139, vcc
	v_add_co_u32_e32 v126, vcc, s22, v138
	s_mov_b32 s22, 0x62000
	s_nop 0
	v_addc_co_u32_e32 v127, vcc, 0, v139, vcc
	v_add_co_u32_e32 v144, vcc, s22, v138
	s_mov_b32 s22, 0x64000
	s_nop 0
	v_addc_co_u32_e32 v145, vcc, 0, v139, vcc
	v_add_co_u32_e32 v146, vcc, s22, v138
	s_mov_b32 s22, 0x66000
	s_nop 0
	v_addc_co_u32_e32 v147, vcc, 0, v139, vcc
	v_add_co_u32_e32 v150, vcc, s22, v138
	s_mov_b32 s22, 0x70000
	s_nop 0
	v_addc_co_u32_e32 v151, vcc, 0, v139, vcc
	v_add_co_u32_e32 v152, vcc, s22, v138
	s_mov_b32 s22, 0x72000
	s_nop 0
	v_addc_co_u32_e32 v153, vcc, 0, v139, vcc
	v_add_co_u32_e32 v154, vcc, s22, v138
	s_mov_b32 s22, 0x74000
	s_nop 0
	v_addc_co_u32_e32 v155, vcc, 0, v139, vcc
	v_add_co_u32_e32 v156, vcc, s22, v138
	s_mov_b32 s22, 0x76000
	s_nop 0
	v_addc_co_u32_e32 v157, vcc, 0, v139, vcc
	v_add_co_u32_e32 v158, vcc, s22, v138
	s_waitcnt vmcnt(48)
	v_add_f32_e32 v96, v96, v210
	v_addc_co_u32_e32 v159, vcc, 0, v139, vcc
	global_load_dword v149, v[112:113], off
	global_load_dword v160, v[114:115], off
	global_load_dword v161, v[116:117], off
	global_load_dword v162, v[118:119], off
	global_load_dword v163, v[120:121], off
	global_load_dword v164, v[122:123], off
	global_load_dword v165, v[124:125], off
	global_load_dword v166, v[126:127], off
	global_load_dword v167, v[144:145], off
	global_load_dword v168, v[146:147], off
	global_load_dword v169, v[150:151], off
	global_load_dword v170, v[152:153], off
	global_load_dword v171, v[154:155], off
	global_load_dword v172, v[156:157], off
	global_load_dword v173, v[158:159], off
	s_waitcnt vmcnt(62)
	v_add_f32_e32 v131, v97, v211
	global_store_dword v[140:141], v96, off offset:128
	v_mul_f32_e32 v96, v128, v96
	v_cvt_pk_bf16_f32 v96, v96, s0
	global_store_short v[142:143], v96, off offset:64
	v_or_b32_e32 v96, 0x820, v130
	v_ashrrev_i32_e32 v97, 31, v96
	v_lshl_add_u64 v[140:141], v[96:97], 2, v[134:135]
	global_store_dword v[140:141], v131, off
	v_mul_f32_e32 v131, v128, v131
	v_cvt_pk_bf16_f32 v131, v131, s0
	v_lshl_add_u64 v[96:97], v[96:97], 1, v[136:137]
	global_store_short v[96:97], v131, off
	v_or_b32_e32 v96, 0x1020, v130
	v_ashrrev_i32_e32 v97, 31, v96
	s_waitcnt vmcnt(62)
	v_add_f32_e32 v98, v98, v212
	v_lshl_add_u64 v[140:141], v[96:97], 2, v[134:135]
	global_store_dword v[140:141], v98, off
	v_mul_f32_e32 v98, v128, v98
	v_cvt_pk_bf16_f32 v98, v98, s0
	v_lshl_add_u64 v[96:97], v[96:97], 1, v[136:137]
	global_store_short v[96:97], v98, off
	v_or_b32_e32 v96, 0x1820, v130
	v_ashrrev_i32_e32 v97, 31, v96
	v_add_f32_e32 v131, v99, v213
	v_lshl_add_u64 v[98:99], v[96:97], 2, v[134:135]
	global_store_dword v[98:99], v131, off
	v_mul_f32_e32 v98, v128, v131
	v_cvt_pk_bf16_f32 v98, v98, s0
	v_lshl_add_u64 v[96:97], v[96:97], 1, v[136:137]
	global_store_short v[96:97], v98, off
	v_or_b32_e32 v96, 0x4020, v130
	v_ashrrev_i32_e32 v97, 31, v96
	v_add_f32_e32 v100, v100, v214
	v_lshl_add_u64 v[98:99], v[96:97], 2, v[134:135]
	global_store_dword v[98:99], v100, off
	v_mul_f32_e32 v98, v128, v100
	v_cvt_pk_bf16_f32 v98, v98, s0
	v_lshl_add_u64 v[96:97], v[96:97], 1, v[136:137]
	global_store_short v[96:97], v98, off
	v_or_b32_e32 v96, 0x4820, v130
	v_ashrrev_i32_e32 v97, 31, v96
	v_add_f32_e32 v100, v101, v215
	v_lshl_add_u64 v[98:99], v[96:97], 2, v[134:135]
	global_store_dword v[98:99], v100, off
	v_mul_f32_e32 v98, v128, v100
	v_cvt_pk_bf16_f32 v98, v98, s0
	v_lshl_add_u64 v[96:97], v[96:97], 1, v[136:137]
	global_store_short v[96:97], v98, off
	v_or_b32_e32 v96, 0x5020, v130
	v_ashrrev_i32_e32 v97, 31, v96
	s_waitcnt vmcnt(62)
	v_add_f32_e32 v100, v102, v216
	v_lshl_add_u64 v[98:99], v[96:97], 2, v[134:135]
	global_store_dword v[98:99], v100, off
	v_mul_f32_e32 v98, v128, v100
	v_cvt_pk_bf16_f32 v98, v98, s0
	v_lshl_add_u64 v[96:97], v[96:97], 1, v[136:137]
	global_store_short v[96:97], v98, off
	v_or_b32_e32 v96, 0x5820, v130
	v_ashrrev_i32_e32 v97, 31, v96
	v_add_f32_e32 v100, v103, v220
	v_lshl_add_u64 v[98:99], v[96:97], 2, v[134:135]
	global_store_dword v[98:99], v100, off
	v_mul_f32_e32 v98, v128, v100
	v_cvt_pk_bf16_f32 v98, v98, s0
	v_lshl_add_u64 v[96:97], v[96:97], 1, v[136:137]
	global_store_short v[96:97], v98, off
	v_or_b32_e32 v96, 0x8020, v130
	v_ashrrev_i32_e32 v97, 31, v96
	v_add_f32_e32 v100, v104, v221
	v_lshl_add_u64 v[98:99], v[96:97], 2, v[134:135]
	global_store_dword v[98:99], v100, off
	v_mul_f32_e32 v98, v128, v100
	v_cvt_pk_bf16_f32 v98, v98, s0
	v_lshl_add_u64 v[96:97], v[96:97], 1, v[136:137]
	global_store_short v[96:97], v98, off
	v_or_b32_e32 v96, 0x8820, v130
	v_ashrrev_i32_e32 v97, 31, v96
	v_add_f32_e32 v100, v105, v223
	v_lshl_add_u64 v[98:99], v[96:97], 2, v[134:135]
	global_store_dword v[98:99], v100, off
	v_mul_f32_e32 v98, v128, v100
	v_cvt_pk_bf16_f32 v98, v98, s0
	v_lshl_add_u64 v[96:97], v[96:97], 1, v[136:137]
	global_store_short v[96:97], v98, off
	v_or_b32_e32 v96, 0x9020, v130
	v_ashrrev_i32_e32 v97, 31, v96
	v_add_f32_e32 v100, v106, v224
	v_lshl_add_u64 v[98:99], v[96:97], 2, v[134:135]
	global_store_dword v[98:99], v100, off
	v_mul_f32_e32 v98, v128, v100
	v_cvt_pk_bf16_f32 v98, v98, s0
	v_lshl_add_u64 v[96:97], v[96:97], 1, v[136:137]
	global_store_short v[96:97], v98, off
	v_or_b32_e32 v96, 0x9820, v130
	v_ashrrev_i32_e32 v97, 31, v96
	v_add_f32_e32 v100, v107, v225
	v_lshl_add_u64 v[98:99], v[96:97], 2, v[134:135]
	global_store_dword v[98:99], v100, off
	v_mul_f32_e32 v98, v128, v100
	v_cvt_pk_bf16_f32 v98, v98, s0
	v_lshl_add_u64 v[96:97], v[96:97], 1, v[136:137]
	global_store_short v[96:97], v98, off
	v_or_b32_e32 v96, 0xc020, v130
	v_ashrrev_i32_e32 v97, 31, v96
	v_add_f32_e32 v100, v108, v222
	v_lshl_add_u64 v[98:99], v[96:97], 2, v[134:135]
	global_store_dword v[98:99], v100, off
	v_mul_f32_e32 v98, v128, v100
	v_cvt_pk_bf16_f32 v98, v98, s0
	v_lshl_add_u64 v[96:97], v[96:97], 1, v[136:137]
	global_store_short v[96:97], v98, off
	v_or_b32_e32 v96, 0xc820, v130
	v_ashrrev_i32_e32 v97, 31, v96
	v_add_f32_e32 v100, v109, v218
	v_lshl_add_u64 v[98:99], v[96:97], 2, v[134:135]
	global_store_dword v[98:99], v100, off
	v_mul_f32_e32 v98, v128, v100
	v_cvt_pk_bf16_f32 v98, v98, s0
	v_lshl_add_u64 v[96:97], v[96:97], 1, v[136:137]
	global_store_short v[96:97], v98, off
	v_or_b32_e32 v96, 0xd020, v130
	v_ashrrev_i32_e32 v97, 31, v96
	s_waitcnt vmcnt(62)
	v_add_f32_e32 v100, v110, v217
	v_lshl_add_u64 v[98:99], v[96:97], 2, v[134:135]
	global_store_dword v[98:99], v100, off
	v_mul_f32_e32 v98, v128, v100
	v_cvt_pk_bf16_f32 v98, v98, s0
	v_lshl_add_u64 v[96:97], v[96:97], 1, v[136:137]
	global_store_short v[96:97], v98, off
	v_or_b32_e32 v96, 0xd820, v130
	v_ashrrev_i32_e32 v97, 31, v96
	v_add_f32_e32 v100, v111, v219
	v_lshl_add_u64 v[98:99], v[96:97], 2, v[134:135]
	global_store_dword v[98:99], v100, off
	v_mul_f32_e32 v98, v128, v100
	v_cvt_pk_bf16_f32 v98, v98, s0
	v_lshl_add_u64 v[96:97], v[96:97], 1, v[136:137]
	global_store_short v[96:97], v98, off
	v_or_b32_e32 v96, 0x10000, v130
	v_ashrrev_i32_e32 v97, 31, v96
	v_lshlrev_b64 v[140:141], 2, v[96:97]
	v_lshl_add_u64 v[98:99], v[132:133], 0, v[140:141]
	global_load_dword v131, v[98:99], off offset:128
	s_nop 0
	global_load_dword v112, v[112:113], off offset:128
	s_nop 0
	global_load_dword v111, v[114:115], off offset:128
	global_load_dword v110, v[116:117], off offset:128
	global_load_dword v109, v[118:119], off offset:128
	global_load_dword v108, v[120:121], off offset:128
	global_load_dword v107, v[122:123], off offset:128
	global_load_dword v106, v[124:125], off offset:128
	global_load_dword v105, v[126:127], off offset:128
	global_load_dword v104, v[144:145], off offset:128
	global_load_dword v103, v[146:147], off offset:128
	global_load_dword v102, v[150:151], off offset:128
	global_load_dword v101, v[152:153], off offset:128
	global_load_dword v100, v[154:155], off offset:128
	global_load_dword v99, v[156:157], off offset:128
	global_load_dword v98, v[158:159], off offset:128
	s_waitcnt vmcnt(62)
	v_add_f32_e32 v80, v80, v148
	v_lshl_add_u64 v[114:115], v[134:135], 0, v[140:141]
	global_store_dword v[114:115], v80, off
	v_mul_f32_e32 v80, v209, v80
	v_cvt_pk_bf16_f32 v80, v80, s0
	v_lshl_add_u64 v[96:97], v[96:97], 1, v[136:137]
	global_store_short v[96:97], v80, off
	v_or_b32_e32 v80, 0x10800, v130
	v_add_f32_e32 v113, v81, v149
	v_ashrrev_i32_e32 v81, 31, v80
	v_lshl_add_u64 v[96:97], v[80:81], 2, v[134:135]
	global_store_dword v[96:97], v113, off
	v_mul_f32_e32 v96, v209, v113
	v_cvt_pk_bf16_f32 v96, v96, s0
	v_lshl_add_u64 v[80:81], v[80:81], 1, v[136:137]
	global_store_short v[80:81], v96, off
	v_or_b32_e32 v80, 0x11000, v130
	v_ashrrev_i32_e32 v81, 31, v80
	s_waitcnt vmcnt(62)
	v_add_f32_e32 v82, v82, v160
	v_lshl_add_u64 v[96:97], v[80:81], 2, v[134:135]
	global_store_dword v[96:97], v82, off
	v_mul_f32_e32 v82, v209, v82
	v_cvt_pk_bf16_f32 v82, v82, s0
	v_lshl_add_u64 v[80:81], v[80:81], 1, v[136:137]
	global_store_short v[80:81], v82, off
	v_or_b32_e32 v80, 0x11800, v130
	v_ashrrev_i32_e32 v81, 31, v80
	v_add_f32_e32 v96, v83, v161
	v_lshl_add_u64 v[82:83], v[80:81], 2, v[134:135]
	global_store_dword v[82:83], v96, off
	v_mul_f32_e32 v82, v209, v96
	v_cvt_pk_bf16_f32 v82, v82, s0
	v_lshl_add_u64 v[80:81], v[80:81], 1, v[136:137]
	global_store_short v[80:81], v82, off
	v_or_b32_e32 v80, 0x14000, v130
	v_ashrrev_i32_e32 v81, 31, v80
	v_add_f32_e32 v84, v84, v162
	v_lshl_add_u64 v[82:83], v[80:81], 2, v[134:135]
	global_store_dword v[82:83], v84, off
	v_mul_f32_e32 v82, v209, v84
	v_cvt_pk_bf16_f32 v82, v82, s0
	v_lshl_add_u64 v[80:81], v[80:81], 1, v[136:137]
	global_store_short v[80:81], v82, off
	v_or_b32_e32 v80, 0x14800, v130
	v_ashrrev_i32_e32 v81, 31, v80
	v_add_f32_e32 v84, v85, v163
	v_lshl_add_u64 v[82:83], v[80:81], 2, v[134:135]
	global_store_dword v[82:83], v84, off
	v_mul_f32_e32 v82, v209, v84
	v_cvt_pk_bf16_f32 v82, v82, s0
	v_lshl_add_u64 v[80:81], v[80:81], 1, v[136:137]
	global_store_short v[80:81], v82, off
	v_or_b32_e32 v80, 0x15000, v130
	v_ashrrev_i32_e32 v81, 31, v80
	s_waitcnt vmcnt(62)
	v_add_f32_e32 v84, v86, v164
	v_lshl_add_u64 v[82:83], v[80:81], 2, v[134:135]
	global_store_dword v[82:83], v84, off
	v_mul_f32_e32 v82, v209, v84
	v_cvt_pk_bf16_f32 v82, v82, s0
	v_lshl_add_u64 v[80:81], v[80:81], 1, v[136:137]
	global_store_short v[80:81], v82, off
	v_or_b32_e32 v80, 0x15800, v130
	v_ashrrev_i32_e32 v81, 31, v80
	v_add_f32_e32 v84, v87, v165
	v_lshl_add_u64 v[82:83], v[80:81], 2, v[134:135]
	global_store_dword v[82:83], v84, off
	v_mul_f32_e32 v82, v209, v84
	v_cvt_pk_bf16_f32 v82, v82, s0
	v_lshl_add_u64 v[80:81], v[80:81], 1, v[136:137]
	global_store_short v[80:81], v82, off
	v_or_b32_e32 v80, 0x18000, v130
	v_ashrrev_i32_e32 v81, 31, v80
	v_add_f32_e32 v84, v88, v166
	v_lshl_add_u64 v[82:83], v[80:81], 2, v[134:135]
	global_store_dword v[82:83], v84, off
	v_mul_f32_e32 v82, v209, v84
	v_cvt_pk_bf16_f32 v82, v82, s0
	v_lshl_add_u64 v[80:81], v[80:81], 1, v[136:137]
	global_store_short v[80:81], v82, off
	v_or_b32_e32 v80, 0x18800, v130
	v_ashrrev_i32_e32 v81, 31, v80
	v_add_f32_e32 v84, v89, v167
	v_lshl_add_u64 v[82:83], v[80:81], 2, v[134:135]
	global_store_dword v[82:83], v84, off
	v_mul_f32_e32 v82, v209, v84
	v_cvt_pk_bf16_f32 v82, v82, s0
	v_lshl_add_u64 v[80:81], v[80:81], 1, v[136:137]
	global_store_short v[80:81], v82, off
	v_or_b32_e32 v80, 0x19000, v130
	v_ashrrev_i32_e32 v81, 31, v80
	v_add_f32_e32 v84, v90, v168
	v_lshl_add_u64 v[82:83], v[80:81], 2, v[134:135]
	global_store_dword v[82:83], v84, off
	v_mul_f32_e32 v82, v209, v84
	v_cvt_pk_bf16_f32 v82, v82, s0
	v_lshl_add_u64 v[80:81], v[80:81], 1, v[136:137]
	global_store_short v[80:81], v82, off
	v_or_b32_e32 v80, 0x19800, v130
	v_ashrrev_i32_e32 v81, 31, v80
	v_add_f32_e32 v84, v91, v169
	v_lshl_add_u64 v[82:83], v[80:81], 2, v[134:135]
	global_store_dword v[82:83], v84, off
	v_mul_f32_e32 v82, v209, v84
	v_cvt_pk_bf16_f32 v82, v82, s0
	v_lshl_add_u64 v[80:81], v[80:81], 1, v[136:137]
	global_store_short v[80:81], v82, off
	v_or_b32_e32 v80, 0x1c000, v130
	v_ashrrev_i32_e32 v81, 31, v80
	v_add_f32_e32 v84, v92, v170
	v_lshl_add_u64 v[82:83], v[80:81], 2, v[134:135]
	global_store_dword v[82:83], v84, off
	v_mul_f32_e32 v82, v209, v84
	v_cvt_pk_bf16_f32 v82, v82, s0
	v_lshl_add_u64 v[80:81], v[80:81], 1, v[136:137]
	global_store_short v[80:81], v82, off
	v_or_b32_e32 v80, 0x1c800, v130
	v_ashrrev_i32_e32 v81, 31, v80
	v_add_f32_e32 v84, v93, v171
	v_lshl_add_u64 v[82:83], v[80:81], 2, v[134:135]
	global_store_dword v[82:83], v84, off
	v_mul_f32_e32 v82, v209, v84
	v_cvt_pk_bf16_f32 v82, v82, s0
	v_lshl_add_u64 v[80:81], v[80:81], 1, v[136:137]
	global_store_short v[80:81], v82, off
	v_or_b32_e32 v80, 0x1d000, v130
	v_ashrrev_i32_e32 v81, 31, v80
	s_waitcnt vmcnt(62)
	v_add_f32_e32 v84, v94, v172
	v_lshl_add_u64 v[82:83], v[80:81], 2, v[134:135]
	global_store_dword v[82:83], v84, off
	v_mul_f32_e32 v82, v209, v84
	v_cvt_pk_bf16_f32 v82, v82, s0
	v_lshl_add_u64 v[80:81], v[80:81], 1, v[136:137]
	global_store_short v[80:81], v82, off
	v_or_b32_e32 v80, 0x1d800, v130
	v_ashrrev_i32_e32 v81, 31, v80
	v_add_f32_e32 v84, v95, v173
	v_lshl_add_u64 v[82:83], v[80:81], 2, v[134:135]
	global_store_dword v[82:83], v84, off
	v_mul_f32_e32 v82, v209, v84
	v_cvt_pk_bf16_f32 v82, v82, s0
	v_lshl_add_u64 v[80:81], v[80:81], 1, v[136:137]
	global_store_short v[80:81], v82, off
	v_add_co_u32_e32 v80, vcc, s50, v138
	s_mov_b32 s22, 0xb4000
	s_nop 0
	v_addc_co_u32_e32 v81, vcc, 0, v139, vcc
	global_load_dword v142, v[80:81], off
	v_add_co_u32_e32 v80, vcc, s2, v138
	v_or_b32_e32 v126, 0x10020, v130
	s_nop 0
	v_addc_co_u32_e32 v81, vcc, 0, v139, vcc
	v_add_co_u32_e32 v82, vcc, s36, v138
	v_ashrrev_i32_e32 v127, 31, v126
	s_nop 0
	v_addc_co_u32_e32 v83, vcc, 0, v139, vcc
	v_add_co_u32_e32 v84, vcc, s37, v138
	s_waitcnt vmcnt(48)
	v_add_f32_e32 v64, v64, v131
	v_addc_co_u32_e32 v85, vcc, 0, v139, vcc
	v_add_co_u32_e32 v86, vcc, s38, v138
	v_lshl_add_u64 v[140:141], v[126:127], 2, v[134:135]
	s_nop 0
	v_addc_co_u32_e32 v87, vcc, 0, v139, vcc
	v_add_co_u32_e32 v88, vcc, s39, v138
	global_load_dword v143, v[80:81], off
	global_load_dword v144, v[82:83], off
	global_load_dword v145, v[84:85], off
	global_load_dword v146, v[86:87], off
	v_addc_co_u32_e32 v89, vcc, 0, v139, vcc
	v_add_co_u32_e32 v90, vcc, s96, v138
	global_load_dword v147, v[88:89], off
	s_nop 0
	v_addc_co_u32_e32 v91, vcc, 0, v139, vcc
	v_add_co_u32_e32 v92, vcc, s97, v138
	global_load_dword v148, v[90:91], off
	s_nop 0
	v_addc_co_u32_e32 v93, vcc, 0, v139, vcc
	v_add_co_u32_e32 v94, vcc, s3, v138
	global_load_dword v149, v[92:93], off
	s_nop 0
	v_addc_co_u32_e32 v95, vcc, 0, v139, vcc
	v_add_co_u32_e32 v96, vcc, s4, v138
	global_load_dword v150, v[94:95], off
	s_nop 0
	v_addc_co_u32_e32 v97, vcc, 0, v139, vcc
	v_add_co_u32_e32 v114, vcc, s5, v138
	global_load_dword v151, v[96:97], off
	s_nop 0
	v_addc_co_u32_e32 v115, vcc, 0, v139, vcc
	v_add_co_u32_e32 v116, vcc, s45, v138
	global_load_dword v152, v[114:115], off
	s_nop 0
	v_addc_co_u32_e32 v117, vcc, 0, v139, vcc
	v_add_co_u32_e32 v118, vcc, s54, v138
	global_load_dword v153, v[116:117], off
	s_nop 0
	v_addc_co_u32_e32 v119, vcc, 0, v139, vcc
	v_add_co_u32_e32 v120, vcc, s55, v138
	global_load_dword v154, v[118:119], off
	s_nop 0
	v_addc_co_u32_e32 v121, vcc, 0, v139, vcc
	v_add_co_u32_e32 v122, vcc, s22, v138
	s_mov_b32 s22, 0xb6000
	s_nop 0
	v_addc_co_u32_e32 v123, vcc, 0, v139, vcc
	v_add_co_u32_e32 v124, vcc, s22, v138
	global_load_dword v155, v[120:121], off
	global_load_dword v156, v[122:123], off
	v_addc_co_u32_e32 v125, vcc, 0, v139, vcc
	global_load_dword v157, v[124:125], off
	v_lshl_add_u64 v[126:127], v[126:127], 1, v[136:137]
	global_store_dword v[140:141], v64, off
	v_mul_f32_e32 v64, v128, v64
	v_cvt_pk_bf16_f32 v64, v64, s0
	global_store_short v[126:127], v64, off
	v_or_b32_e32 v64, 0x10820, v130
	s_waitcnt vmcnt(62)
	v_add_f32_e32 v126, v65, v112
	v_ashrrev_i32_e32 v65, 31, v64
	v_lshl_add_u64 v[112:113], v[64:65], 2, v[134:135]
	global_store_dword v[112:113], v126, off
	v_mul_f32_e32 v112, v128, v126
	v_cvt_pk_bf16_f32 v112, v112, s0
	v_lshl_add_u64 v[64:65], v[64:65], 1, v[136:137]
	global_store_short v[64:65], v112, off
	v_or_b32_e32 v64, 0x11020, v130
	v_ashrrev_i32_e32 v65, 31, v64
	v_add_f32_e32 v66, v66, v111
	v_lshl_add_u64 v[112:113], v[64:65], 2, v[134:135]
	global_store_dword v[112:113], v66, off
	v_mul_f32_e32 v66, v128, v66
	v_cvt_pk_bf16_f32 v66, v66, s0
	v_lshl_add_u64 v[64:65], v[64:65], 1, v[136:137]
	global_store_short v[64:65], v66, off
	v_or_b32_e32 v64, 0x11820, v130
	v_ashrrev_i32_e32 v65, 31, v64
	v_add_f32_e32 v110, v67, v110
	v_lshl_add_u64 v[66:67], v[64:65], 2, v[134:135]
	global_store_dword v[66:67], v110, off
	v_mul_f32_e32 v66, v128, v110
	v_cvt_pk_bf16_f32 v66, v66, s0
	v_lshl_add_u64 v[64:65], v[64:65], 1, v[136:137]
	global_store_short v[64:65], v66, off
	v_or_b32_e32 v64, 0x14020, v130
	v_ashrrev_i32_e32 v65, 31, v64
	s_waitcnt vmcnt(62)
	v_add_f32_e32 v68, v68, v109
	v_lshl_add_u64 v[66:67], v[64:65], 2, v[134:135]
	global_store_dword v[66:67], v68, off
	v_mul_f32_e32 v66, v128, v68
	v_cvt_pk_bf16_f32 v66, v66, s0
	v_lshl_add_u64 v[64:65], v[64:65], 1, v[136:137]
	global_store_short v[64:65], v66, off
	v_or_b32_e32 v64, 0x14820, v130
	v_ashrrev_i32_e32 v65, 31, v64
	v_add_f32_e32 v68, v69, v108
	v_lshl_add_u64 v[66:67], v[64:65], 2, v[134:135]
	global_store_dword v[66:67], v68, off
	v_mul_f32_e32 v66, v128, v68
	v_cvt_pk_bf16_f32 v66, v66, s0
	v_lshl_add_u64 v[64:65], v[64:65], 1, v[136:137]
	global_store_short v[64:65], v66, off
	v_or_b32_e32 v64, 0x15020, v130
	v_ashrrev_i32_e32 v65, 31, v64
	v_add_f32_e32 v68, v70, v107
	v_lshl_add_u64 v[66:67], v[64:65], 2, v[134:135]
	global_store_dword v[66:67], v68, off
	v_mul_f32_e32 v66, v128, v68
	v_cvt_pk_bf16_f32 v66, v66, s0
	v_lshl_add_u64 v[64:65], v[64:65], 1, v[136:137]
	global_store_short v[64:65], v66, off
	v_or_b32_e32 v64, 0x15820, v130
	v_ashrrev_i32_e32 v65, 31, v64
	v_add_f32_e32 v68, v71, v106
	v_lshl_add_u64 v[66:67], v[64:65], 2, v[134:135]
	global_store_dword v[66:67], v68, off
	v_mul_f32_e32 v66, v128, v68
	v_cvt_pk_bf16_f32 v66, v66, s0
	v_lshl_add_u64 v[64:65], v[64:65], 1, v[136:137]
	global_store_short v[64:65], v66, off
	v_or_b32_e32 v64, 0x18020, v130
	v_ashrrev_i32_e32 v65, 31, v64
	v_add_f32_e32 v68, v72, v105
	v_lshl_add_u64 v[66:67], v[64:65], 2, v[134:135]
	global_store_dword v[66:67], v68, off
	v_mul_f32_e32 v66, v128, v68
	v_cvt_pk_bf16_f32 v66, v66, s0
	v_lshl_add_u64 v[64:65], v[64:65], 1, v[136:137]
	global_store_short v[64:65], v66, off
	v_or_b32_e32 v64, 0x18820, v130
	v_ashrrev_i32_e32 v65, 31, v64
	v_add_f32_e32 v68, v73, v104
	v_lshl_add_u64 v[66:67], v[64:65], 2, v[134:135]
	global_store_dword v[66:67], v68, off
	v_mul_f32_e32 v66, v128, v68
	v_cvt_pk_bf16_f32 v66, v66, s0
	v_lshl_add_u64 v[64:65], v[64:65], 1, v[136:137]
	global_store_short v[64:65], v66, off
	v_or_b32_e32 v64, 0x19020, v130
	v_ashrrev_i32_e32 v65, 31, v64
	s_waitcnt vmcnt(62)
	v_add_f32_e32 v68, v74, v103
	v_lshl_add_u64 v[66:67], v[64:65], 2, v[134:135]
	global_store_dword v[66:67], v68, off
	v_mul_f32_e32 v66, v128, v68
	v_cvt_pk_bf16_f32 v66, v66, s0
	v_lshl_add_u64 v[64:65], v[64:65], 1, v[136:137]
	global_store_short v[64:65], v66, off
	v_or_b32_e32 v64, 0x19820, v130
	v_ashrrev_i32_e32 v65, 31, v64
	v_add_f32_e32 v68, v75, v102
	v_lshl_add_u64 v[66:67], v[64:65], 2, v[134:135]
	global_store_dword v[66:67], v68, off
	v_mul_f32_e32 v66, v128, v68
	v_cvt_pk_bf16_f32 v66, v66, s0
	v_lshl_add_u64 v[64:65], v[64:65], 1, v[136:137]
	global_store_short v[64:65], v66, off
	v_or_b32_e32 v64, 0x1c020, v130
	v_ashrrev_i32_e32 v65, 31, v64
	v_add_f32_e32 v68, v76, v101
	v_lshl_add_u64 v[66:67], v[64:65], 2, v[134:135]
	global_store_dword v[66:67], v68, off
	v_mul_f32_e32 v66, v128, v68
	v_cvt_pk_bf16_f32 v66, v66, s0
	v_lshl_add_u64 v[64:65], v[64:65], 1, v[136:137]
	global_store_short v[64:65], v66, off
	v_or_b32_e32 v64, 0x1c820, v130
	v_ashrrev_i32_e32 v65, 31, v64
	v_add_f32_e32 v68, v77, v100
	v_lshl_add_u64 v[66:67], v[64:65], 2, v[134:135]
	global_store_dword v[66:67], v68, off
	v_mul_f32_e32 v66, v128, v68
	v_cvt_pk_bf16_f32 v66, v66, s0
	v_lshl_add_u64 v[64:65], v[64:65], 1, v[136:137]
	global_store_short v[64:65], v66, off
	v_or_b32_e32 v64, 0x1d020, v130
	v_ashrrev_i32_e32 v65, 31, v64
	v_add_f32_e32 v68, v78, v99
	v_lshl_add_u64 v[66:67], v[64:65], 2, v[134:135]
	global_store_dword v[66:67], v68, off
	v_mul_f32_e32 v66, v128, v68
	v_cvt_pk_bf16_f32 v66, v66, s0
	v_lshl_add_u64 v[64:65], v[64:65], 1, v[136:137]
	global_store_short v[64:65], v66, off
	v_or_b32_e32 v64, 0x1d820, v130
	v_ashrrev_i32_e32 v65, 31, v64
	v_add_f32_e32 v68, v79, v98
	v_lshl_add_u64 v[66:67], v[64:65], 2, v[134:135]
	global_store_dword v[66:67], v68, off
	v_mul_f32_e32 v66, v128, v68
	v_cvt_pk_bf16_f32 v66, v66, s0
	v_lshl_add_u64 v[64:65], v[64:65], 1, v[136:137]
	global_store_short v[64:65], v66, off
	v_or_b32_e32 v64, 0x20000, v130
	v_ashrrev_i32_e32 v65, 31, v64
	v_lshlrev_b64 v[66:67], 2, v[64:65]
	v_lshl_add_u64 v[68:69], v[132:133], 0, v[66:67]
	s_waitcnt vmcnt(47)
	v_add_f32_e32 v48, v48, v142
	v_lshl_add_u64 v[66:67], v[134:135], 0, v[66:67]
	global_load_dword v102, v[68:69], off offset:128
	global_load_dword v101, v[80:81], off offset:128
	global_load_dword v100, v[82:83], off offset:128
	global_load_dword v99, v[84:85], off offset:128
	global_load_dword v98, v[86:87], off offset:128
	s_nop 0
	global_load_dword v88, v[88:89], off offset:128
	s_nop 0
	global_load_dword v87, v[90:91], off offset:128
	global_load_dword v86, v[92:93], off offset:128
	global_load_dword v85, v[94:95], off offset:128
	global_load_dword v84, v[96:97], off offset:128
	global_load_dword v83, v[114:115], off offset:128
	global_load_dword v82, v[116:117], off offset:128
	global_load_dword v81, v[118:119], off offset:128
	global_load_dword v80, v[120:121], off offset:128
	global_load_dword v79, v[122:123], off offset:128
	global_load_dword v78, v[124:125], off offset:128
	v_lshl_add_u64 v[64:65], v[64:65], 1, v[136:137]
	global_store_dword v[66:67], v48, off
	v_mul_f32_e32 v48, v209, v48
	v_cvt_pk_bf16_f32 v48, v48, s0
	global_store_short v[64:65], v48, off
	v_or_b32_e32 v48, 0x20800, v130
	s_waitcnt vmcnt(62)
	v_add_f32_e32 v66, v49, v143
	v_ashrrev_i32_e32 v49, 31, v48
	v_lshl_add_u64 v[64:65], v[48:49], 2, v[134:135]
	global_store_dword v[64:65], v66, off
	v_mul_f32_e32 v64, v209, v66
	v_cvt_pk_bf16_f32 v64, v64, s0
	v_lshl_add_u64 v[48:49], v[48:49], 1, v[136:137]
	global_store_short v[48:49], v64, off
	v_or_b32_e32 v48, 0x21000, v130
	v_ashrrev_i32_e32 v49, 31, v48
	v_add_f32_e32 v50, v50, v144
	v_lshl_add_u64 v[64:65], v[48:49], 2, v[134:135]
	global_store_dword v[64:65], v50, off
	v_mul_f32_e32 v50, v209, v50
	v_cvt_pk_bf16_f32 v50, v50, s0
	v_lshl_add_u64 v[48:49], v[48:49], 1, v[136:137]
	global_store_short v[48:49], v50, off
	v_or_b32_e32 v48, 0x21800, v130
	v_ashrrev_i32_e32 v49, 31, v48
	v_add_f32_e32 v64, v51, v145
	v_lshl_add_u64 v[50:51], v[48:49], 2, v[134:135]
	global_store_dword v[50:51], v64, off
	v_mul_f32_e32 v50, v209, v64
	v_cvt_pk_bf16_f32 v50, v50, s0
	v_lshl_add_u64 v[48:49], v[48:49], 1, v[136:137]
	global_store_short v[48:49], v50, off
	v_or_b32_e32 v48, 0x24000, v130
	v_ashrrev_i32_e32 v49, 31, v48
	s_waitcnt vmcnt(62)
	v_add_f32_e32 v52, v52, v146
	v_lshl_add_u64 v[50:51], v[48:49], 2, v[134:135]
	global_store_dword v[50:51], v52, off
	v_mul_f32_e32 v50, v209, v52
	v_cvt_pk_bf16_f32 v50, v50, s0
	v_lshl_add_u64 v[48:49], v[48:49], 1, v[136:137]
	global_store_short v[48:49], v50, off
	v_or_b32_e32 v48, 0x24800, v130
	v_ashrrev_i32_e32 v49, 31, v48
	v_add_f32_e32 v52, v53, v147
	v_lshl_add_u64 v[50:51], v[48:49], 2, v[134:135]
	global_store_dword v[50:51], v52, off
	v_mul_f32_e32 v50, v209, v52
	v_cvt_pk_bf16_f32 v50, v50, s0
	v_lshl_add_u64 v[48:49], v[48:49], 1, v[136:137]
	global_store_short v[48:49], v50, off
	v_or_b32_e32 v48, 0x25000, v130
	v_ashrrev_i32_e32 v49, 31, v48
	v_add_f32_e32 v52, v54, v148
	v_lshl_add_u64 v[50:51], v[48:49], 2, v[134:135]
	global_store_dword v[50:51], v52, off
	v_mul_f32_e32 v50, v209, v52
	v_cvt_pk_bf16_f32 v50, v50, s0
	v_lshl_add_u64 v[48:49], v[48:49], 1, v[136:137]
	global_store_short v[48:49], v50, off
	v_or_b32_e32 v48, 0x25800, v130
	v_ashrrev_i32_e32 v49, 31, v48
	v_add_f32_e32 v52, v55, v149
	v_lshl_add_u64 v[50:51], v[48:49], 2, v[134:135]
	global_store_dword v[50:51], v52, off
	v_mul_f32_e32 v50, v209, v52
	v_cvt_pk_bf16_f32 v50, v50, s0
	v_lshl_add_u64 v[48:49], v[48:49], 1, v[136:137]
	global_store_short v[48:49], v50, off
	v_or_b32_e32 v48, 0x28000, v130
	v_ashrrev_i32_e32 v49, 31, v48
	v_add_f32_e32 v52, v56, v150
	v_lshl_add_u64 v[50:51], v[48:49], 2, v[134:135]
	global_store_dword v[50:51], v52, off
	v_mul_f32_e32 v50, v209, v52
	v_cvt_pk_bf16_f32 v50, v50, s0
	v_lshl_add_u64 v[48:49], v[48:49], 1, v[136:137]
	global_store_short v[48:49], v50, off
	v_or_b32_e32 v48, 0x28800, v130
	v_ashrrev_i32_e32 v49, 31, v48
	v_add_f32_e32 v52, v57, v151
	v_lshl_add_u64 v[50:51], v[48:49], 2, v[134:135]
	global_store_dword v[50:51], v52, off
	v_mul_f32_e32 v50, v209, v52
	v_cvt_pk_bf16_f32 v50, v50, s0
	v_lshl_add_u64 v[48:49], v[48:49], 1, v[136:137]
	global_store_short v[48:49], v50, off
	v_or_b32_e32 v48, 0x29000, v130
	v_ashrrev_i32_e32 v49, 31, v48
	s_waitcnt vmcnt(62)
	v_add_f32_e32 v52, v58, v152
	v_lshl_add_u64 v[50:51], v[48:49], 2, v[134:135]
	global_store_dword v[50:51], v52, off
	v_mul_f32_e32 v50, v209, v52
	v_cvt_pk_bf16_f32 v50, v50, s0
	v_lshl_add_u64 v[48:49], v[48:49], 1, v[136:137]
	global_store_short v[48:49], v50, off
	v_or_b32_e32 v48, 0x29800, v130
	v_ashrrev_i32_e32 v49, 31, v48
	v_add_f32_e32 v52, v59, v153
	v_lshl_add_u64 v[50:51], v[48:49], 2, v[134:135]
	global_store_dword v[50:51], v52, off
	v_mul_f32_e32 v50, v209, v52
	v_cvt_pk_bf16_f32 v50, v50, s0
	v_lshl_add_u64 v[48:49], v[48:49], 1, v[136:137]
	global_store_short v[48:49], v50, off
	v_or_b32_e32 v48, 0x2c000, v130
	v_ashrrev_i32_e32 v49, 31, v48
	v_add_f32_e32 v52, v60, v154
	v_lshl_add_u64 v[50:51], v[48:49], 2, v[134:135]
	global_store_dword v[50:51], v52, off
	v_mul_f32_e32 v50, v209, v52
	v_cvt_pk_bf16_f32 v50, v50, s0
	v_lshl_add_u64 v[48:49], v[48:49], 1, v[136:137]
	global_store_short v[48:49], v50, off
	v_or_b32_e32 v48, 0x2c800, v130
	v_ashrrev_i32_e32 v49, 31, v48
	v_add_f32_e32 v52, v61, v155
	v_lshl_add_u64 v[50:51], v[48:49], 2, v[134:135]
	global_store_dword v[50:51], v52, off
	v_mul_f32_e32 v50, v209, v52
	v_cvt_pk_bf16_f32 v50, v50, s0
	v_lshl_add_u64 v[48:49], v[48:49], 1, v[136:137]
	global_store_short v[48:49], v50, off
	v_or_b32_e32 v48, 0x2d000, v130
	v_ashrrev_i32_e32 v49, 31, v48
	v_add_f32_e32 v52, v62, v156
	v_lshl_add_u64 v[50:51], v[48:49], 2, v[134:135]
	global_store_dword v[50:51], v52, off
	v_mul_f32_e32 v50, v209, v52
	v_cvt_pk_bf16_f32 v50, v50, s0
	v_lshl_add_u64 v[48:49], v[48:49], 1, v[136:137]
	global_store_short v[48:49], v50, off
	v_or_b32_e32 v48, 0x2d800, v130
	v_ashrrev_i32_e32 v49, 31, v48
	v_add_f32_e32 v52, v63, v157
	v_lshl_add_u64 v[50:51], v[48:49], 2, v[134:135]
	global_store_dword v[50:51], v52, off
	v_mul_f32_e32 v50, v209, v52
	v_cvt_pk_bf16_f32 v50, v50, s0
	v_lshl_add_u64 v[48:49], v[48:49], 1, v[136:137]
	s_mov_b32 s22, 0xc0000
	global_store_short v[48:49], v50, off
	v_add_co_u32_e32 v48, vcc, s22, v138
	s_mov_b32 s22, 0xc2000
	s_nop 0
	v_addc_co_u32_e32 v49, vcc, 0, v139, vcc
	global_load_dword v89, v[48:49], off
	v_add_co_u32_e32 v48, vcc, s22, v138
	v_or_b32_e32 v110, 0x20020, v130
	s_nop 0
	v_addc_co_u32_e32 v49, vcc, 0, v139, vcc
	v_add_co_u32_e32 v50, vcc, s76, v138
	v_ashrrev_i32_e32 v111, 31, v110
	s_nop 0
	v_addc_co_u32_e32 v51, vcc, 0, v139, vcc
	v_add_co_u32_e32 v52, vcc, s77, v138
	s_waitcnt vmcnt(48)
	v_add_f32_e32 v32, v32, v102
	v_addc_co_u32_e32 v53, vcc, 0, v139, vcc
	v_add_co_u32_e32 v54, vcc, s78, v138
	v_lshl_add_u64 v[112:113], v[110:111], 2, v[134:135]
	s_nop 0
	v_addc_co_u32_e32 v55, vcc, 0, v139, vcc
	v_add_co_u32_e32 v56, vcc, s79, v138
	global_load_dword v90, v[48:49], off
	global_load_dword v91, v[50:51], off
	global_load_dword v92, v[52:53], off
	global_load_dword v93, v[54:55], off
	v_addc_co_u32_e32 v57, vcc, 0, v139, vcc
	v_add_co_u32_e32 v58, vcc, s80, v138
	global_load_dword v94, v[56:57], off
	s_nop 0
	v_addc_co_u32_e32 v59, vcc, 0, v139, vcc
	v_add_co_u32_e32 v60, vcc, s81, v138
	global_load_dword v95, v[58:59], off
	s_nop 0
	v_addc_co_u32_e32 v61, vcc, 0, v139, vcc
	v_add_co_u32_e32 v62, vcc, s82, v138
	global_load_dword v96, v[60:61], off
	s_nop 0
	v_addc_co_u32_e32 v63, vcc, 0, v139, vcc
	v_add_co_u32_e32 v64, vcc, s83, v138
	global_load_dword v97, v[62:63], off
	s_nop 0
	v_addc_co_u32_e32 v65, vcc, 0, v139, vcc
	v_add_co_u32_e32 v66, vcc, s84, v138
	global_load_dword v103, v[64:65], off
	s_nop 0
	v_addc_co_u32_e32 v67, vcc, 0, v139, vcc
	v_add_co_u32_e32 v68, vcc, s85, v138
	global_load_dword v104, v[66:67], off
	s_nop 0
	v_addc_co_u32_e32 v69, vcc, 0, v139, vcc
	v_add_co_u32_e32 v70, vcc, s86, v138
	global_load_dword v105, v[68:69], off
	s_nop 0
	v_addc_co_u32_e32 v71, vcc, 0, v139, vcc
	v_add_co_u32_e32 v72, vcc, s87, v138
	global_load_dword v106, v[70:71], off
	s_nop 0
	v_addc_co_u32_e32 v73, vcc, 0, v139, vcc
	v_add_co_u32_e32 v74, vcc, s88, v138
	global_load_dword v107, v[72:73], off
	s_nop 0
	v_addc_co_u32_e32 v75, vcc, 0, v139, vcc
	v_add_co_u32_e32 v76, vcc, s89, v138
	global_load_dword v108, v[74:75], off
	s_nop 0
	v_addc_co_u32_e32 v77, vcc, 0, v139, vcc
	global_load_dword v109, v[76:77], off
	v_lshl_add_u64 v[110:111], v[110:111], 1, v[136:137]
	global_store_dword v[112:113], v32, off
	v_mul_f32_e32 v32, v128, v32
	v_cvt_pk_bf16_f32 v32, v32, s0
	global_store_short v[110:111], v32, off
	v_or_b32_e32 v32, 0x20820, v130
	s_waitcnt vmcnt(62)
	v_add_f32_e32 v101, v33, v101
	v_ashrrev_i32_e32 v33, 31, v32
	v_lshl_add_u64 v[110:111], v[32:33], 2, v[134:135]
	global_store_dword v[110:111], v101, off
	v_mul_f32_e32 v101, v128, v101
	v_cvt_pk_bf16_f32 v101, v101, s0
	v_lshl_add_u64 v[32:33], v[32:33], 1, v[136:137]
	global_store_short v[32:33], v101, off
	v_or_b32_e32 v32, 0x21020, v130
	v_ashrrev_i32_e32 v33, 31, v32
	v_add_f32_e32 v34, v34, v100
	v_lshl_add_u64 v[100:101], v[32:33], 2, v[134:135]
	global_store_dword v[100:101], v34, off
	v_mul_f32_e32 v34, v128, v34
	v_cvt_pk_bf16_f32 v34, v34, s0
	v_lshl_add_u64 v[32:33], v[32:33], 1, v[136:137]
	global_store_short v[32:33], v34, off
	v_or_b32_e32 v32, 0x21820, v130
	v_ashrrev_i32_e32 v33, 31, v32
	v_add_f32_e32 v99, v35, v99
	v_lshl_add_u64 v[34:35], v[32:33], 2, v[134:135]
	global_store_dword v[34:35], v99, off
	v_mul_f32_e32 v34, v128, v99
	v_cvt_pk_bf16_f32 v34, v34, s0
	v_lshl_add_u64 v[32:33], v[32:33], 1, v[136:137]
	global_store_short v[32:33], v34, off
	v_or_b32_e32 v32, 0x24020, v130
	v_ashrrev_i32_e32 v33, 31, v32
	s_waitcnt vmcnt(62)
	v_add_f32_e32 v36, v36, v98
	v_lshl_add_u64 v[34:35], v[32:33], 2, v[134:135]
	global_store_dword v[34:35], v36, off
	v_mul_f32_e32 v34, v128, v36
	v_cvt_pk_bf16_f32 v34, v34, s0
	v_lshl_add_u64 v[32:33], v[32:33], 1, v[136:137]
	global_store_short v[32:33], v34, off
	v_or_b32_e32 v32, 0x24820, v130
	v_ashrrev_i32_e32 v33, 31, v32
	v_add_f32_e32 v36, v37, v88
	v_lshl_add_u64 v[34:35], v[32:33], 2, v[134:135]
	global_store_dword v[34:35], v36, off
	v_mul_f32_e32 v34, v128, v36
	v_cvt_pk_bf16_f32 v34, v34, s0
	v_lshl_add_u64 v[32:33], v[32:33], 1, v[136:137]
	global_store_short v[32:33], v34, off
	v_or_b32_e32 v32, 0x25020, v130
	v_ashrrev_i32_e32 v33, 31, v32
	v_add_f32_e32 v36, v38, v87
	v_lshl_add_u64 v[34:35], v[32:33], 2, v[134:135]
	global_store_dword v[34:35], v36, off
	v_mul_f32_e32 v34, v128, v36
	v_cvt_pk_bf16_f32 v34, v34, s0
	v_lshl_add_u64 v[32:33], v[32:33], 1, v[136:137]
	global_store_short v[32:33], v34, off
	v_or_b32_e32 v32, 0x25820, v130
	v_ashrrev_i32_e32 v33, 31, v32
	v_add_f32_e32 v36, v39, v86
	v_lshl_add_u64 v[34:35], v[32:33], 2, v[134:135]
	global_store_dword v[34:35], v36, off
	v_mul_f32_e32 v34, v128, v36
	v_cvt_pk_bf16_f32 v34, v34, s0
	v_lshl_add_u64 v[32:33], v[32:33], 1, v[136:137]
	global_store_short v[32:33], v34, off
	v_or_b32_e32 v32, 0x28020, v130
	v_ashrrev_i32_e32 v33, 31, v32
	v_add_f32_e32 v36, v40, v85
	v_lshl_add_u64 v[34:35], v[32:33], 2, v[134:135]
	global_store_dword v[34:35], v36, off
	v_mul_f32_e32 v34, v128, v36
	v_cvt_pk_bf16_f32 v34, v34, s0
	v_lshl_add_u64 v[32:33], v[32:33], 1, v[136:137]
	global_store_short v[32:33], v34, off
	v_or_b32_e32 v32, 0x28820, v130
	v_ashrrev_i32_e32 v33, 31, v32
	v_add_f32_e32 v36, v41, v84
	v_lshl_add_u64 v[34:35], v[32:33], 2, v[134:135]
	global_store_dword v[34:35], v36, off
	v_mul_f32_e32 v34, v128, v36
	v_cvt_pk_bf16_f32 v34, v34, s0
	v_lshl_add_u64 v[32:33], v[32:33], 1, v[136:137]
	global_store_short v[32:33], v34, off
	v_or_b32_e32 v32, 0x29020, v130
	v_ashrrev_i32_e32 v33, 31, v32
	s_waitcnt vmcnt(62)
	v_add_f32_e32 v36, v42, v83
	v_lshl_add_u64 v[34:35], v[32:33], 2, v[134:135]
	global_store_dword v[34:35], v36, off
	v_mul_f32_e32 v34, v128, v36
	v_cvt_pk_bf16_f32 v34, v34, s0
	v_lshl_add_u64 v[32:33], v[32:33], 1, v[136:137]
	global_store_short v[32:33], v34, off
	v_or_b32_e32 v32, 0x29820, v130
	v_ashrrev_i32_e32 v33, 31, v32
	v_add_f32_e32 v36, v43, v82
	v_lshl_add_u64 v[34:35], v[32:33], 2, v[134:135]
	global_store_dword v[34:35], v36, off
	v_mul_f32_e32 v34, v128, v36
	v_cvt_pk_bf16_f32 v34, v34, s0
	v_lshl_add_u64 v[32:33], v[32:33], 1, v[136:137]
	global_store_short v[32:33], v34, off
	v_or_b32_e32 v32, 0x2c020, v130
	v_ashrrev_i32_e32 v33, 31, v32
	v_add_f32_e32 v36, v44, v81
	v_lshl_add_u64 v[34:35], v[32:33], 2, v[134:135]
	global_store_dword v[34:35], v36, off
	v_mul_f32_e32 v34, v128, v36
	v_cvt_pk_bf16_f32 v34, v34, s0
	v_lshl_add_u64 v[32:33], v[32:33], 1, v[136:137]
	global_store_short v[32:33], v34, off
	v_or_b32_e32 v32, 0x2c820, v130
	v_ashrrev_i32_e32 v33, 31, v32
	v_add_f32_e32 v36, v45, v80
	v_lshl_add_u64 v[34:35], v[32:33], 2, v[134:135]
	global_store_dword v[34:35], v36, off
	v_mul_f32_e32 v34, v128, v36
	v_cvt_pk_bf16_f32 v34, v34, s0
	v_lshl_add_u64 v[32:33], v[32:33], 1, v[136:137]
	global_store_short v[32:33], v34, off
	v_or_b32_e32 v32, 0x2d020, v130
	v_ashrrev_i32_e32 v33, 31, v32
	v_add_f32_e32 v36, v46, v79
	v_lshl_add_u64 v[34:35], v[32:33], 2, v[134:135]
	global_store_dword v[34:35], v36, off
	v_mul_f32_e32 v34, v128, v36
	v_cvt_pk_bf16_f32 v34, v34, s0
	v_lshl_add_u64 v[32:33], v[32:33], 1, v[136:137]
	global_store_short v[32:33], v34, off
	v_or_b32_e32 v32, 0x2d820, v130
	v_ashrrev_i32_e32 v33, 31, v32
	v_add_f32_e32 v36, v47, v78
	v_lshl_add_u64 v[34:35], v[32:33], 2, v[134:135]
	global_store_dword v[34:35], v36, off
	v_mul_f32_e32 v34, v128, v36
	v_cvt_pk_bf16_f32 v34, v34, s0
	v_lshl_add_u64 v[32:33], v[32:33], 1, v[136:137]
	global_store_short v[32:33], v34, off
	v_or_b32_e32 v32, 0x30000, v130
	v_ashrrev_i32_e32 v33, 31, v32
	v_lshlrev_b64 v[34:35], 2, v[32:33]
	v_lshl_add_u64 v[36:37], v[132:133], 0, v[34:35]
	s_waitcnt vmcnt(47)
	v_add_f32_e32 v16, v16, v89
	v_lshl_add_u64 v[34:35], v[134:135], 0, v[34:35]
	global_load_dword v36, v[36:37], off offset:128
	s_nop 0
	global_load_dword v37, v[48:49], off offset:128
	global_load_dword v38, v[50:51], off offset:128
	global_load_dword v39, v[52:53], off offset:128
	global_load_dword v40, v[54:55], off offset:128
	global_load_dword v41, v[56:57], off offset:128
	global_load_dword v42, v[58:59], off offset:128
	global_load_dword v43, v[60:61], off offset:128
	global_load_dword v44, v[62:63], off offset:128
	global_load_dword v45, v[64:65], off offset:128
	global_load_dword v46, v[66:67], off offset:128
	global_load_dword v47, v[68:69], off offset:128
	global_load_dword v48, v[70:71], off offset:128
	global_load_dword v49, v[72:73], off offset:128
	global_load_dword v50, v[74:75], off offset:128
	global_load_dword v51, v[76:77], off offset:128
	v_lshl_add_u64 v[32:33], v[32:33], 1, v[136:137]
	global_store_dword v[34:35], v16, off
	v_mul_f32_e32 v16, v209, v16
	v_cvt_pk_bf16_f32 v16, v16, s0
	global_store_short v[32:33], v16, off
	v_or_b32_e32 v16, 0x30800, v130
	s_waitcnt vmcnt(62)
	v_add_f32_e32 v34, v17, v90
	v_ashrrev_i32_e32 v17, 31, v16
	v_lshl_add_u64 v[32:33], v[16:17], 2, v[134:135]
	global_store_dword v[32:33], v34, off
	v_mul_f32_e32 v32, v209, v34
	v_cvt_pk_bf16_f32 v32, v32, s0
	v_lshl_add_u64 v[16:17], v[16:17], 1, v[136:137]
	global_store_short v[16:17], v32, off
	v_or_b32_e32 v16, 0x31000, v130
	v_ashrrev_i32_e32 v17, 31, v16
	v_add_f32_e32 v18, v18, v91
	v_lshl_add_u64 v[32:33], v[16:17], 2, v[134:135]
	global_store_dword v[32:33], v18, off
	v_mul_f32_e32 v18, v209, v18
	v_cvt_pk_bf16_f32 v18, v18, s0
	v_lshl_add_u64 v[16:17], v[16:17], 1, v[136:137]
	global_store_short v[16:17], v18, off
	v_or_b32_e32 v16, 0x31800, v130
	v_ashrrev_i32_e32 v17, 31, v16
	v_add_f32_e32 v32, v19, v92
	v_lshl_add_u64 v[18:19], v[16:17], 2, v[134:135]
	global_store_dword v[18:19], v32, off
	v_mul_f32_e32 v18, v209, v32
	v_cvt_pk_bf16_f32 v18, v18, s0
	v_lshl_add_u64 v[16:17], v[16:17], 1, v[136:137]
	global_store_short v[16:17], v18, off
	v_or_b32_e32 v16, 0x34000, v130
	v_ashrrev_i32_e32 v17, 31, v16
	s_waitcnt vmcnt(62)
	v_add_f32_e32 v20, v20, v93
	v_lshl_add_u64 v[18:19], v[16:17], 2, v[134:135]
	global_store_dword v[18:19], v20, off
	v_mul_f32_e32 v18, v209, v20
	v_cvt_pk_bf16_f32 v18, v18, s0
	v_lshl_add_u64 v[16:17], v[16:17], 1, v[136:137]
	global_store_short v[16:17], v18, off
	v_or_b32_e32 v16, 0x34800, v130
	v_ashrrev_i32_e32 v17, 31, v16
	v_add_f32_e32 v20, v21, v94
	v_lshl_add_u64 v[18:19], v[16:17], 2, v[134:135]
	global_store_dword v[18:19], v20, off
	v_mul_f32_e32 v18, v209, v20
	v_cvt_pk_bf16_f32 v18, v18, s0
	v_lshl_add_u64 v[16:17], v[16:17], 1, v[136:137]
	global_store_short v[16:17], v18, off
	v_or_b32_e32 v16, 0x35000, v130
	v_ashrrev_i32_e32 v17, 31, v16
	v_add_f32_e32 v20, v22, v95
	v_lshl_add_u64 v[18:19], v[16:17], 2, v[134:135]
	global_store_dword v[18:19], v20, off
	v_mul_f32_e32 v18, v209, v20
	v_cvt_pk_bf16_f32 v18, v18, s0
	v_lshl_add_u64 v[16:17], v[16:17], 1, v[136:137]
	global_store_short v[16:17], v18, off
	v_or_b32_e32 v16, 0x35800, v130
	v_ashrrev_i32_e32 v17, 31, v16
	v_add_f32_e32 v20, v23, v96
	v_lshl_add_u64 v[18:19], v[16:17], 2, v[134:135]
	global_store_dword v[18:19], v20, off
	v_mul_f32_e32 v18, v209, v20
	v_cvt_pk_bf16_f32 v18, v18, s0
	v_lshl_add_u64 v[16:17], v[16:17], 1, v[136:137]
	global_store_short v[16:17], v18, off
	v_or_b32_e32 v16, 0x38000, v130
	v_ashrrev_i32_e32 v17, 31, v16
	v_add_f32_e32 v20, v24, v97
	v_lshl_add_u64 v[18:19], v[16:17], 2, v[134:135]
	global_store_dword v[18:19], v20, off
	v_mul_f32_e32 v18, v209, v20
	v_cvt_pk_bf16_f32 v18, v18, s0
	v_lshl_add_u64 v[16:17], v[16:17], 1, v[136:137]
	global_store_short v[16:17], v18, off
	v_or_b32_e32 v16, 0x38800, v130
	v_ashrrev_i32_e32 v17, 31, v16
	v_add_f32_e32 v20, v25, v103
	v_lshl_add_u64 v[18:19], v[16:17], 2, v[134:135]
	global_store_dword v[18:19], v20, off
	v_mul_f32_e32 v18, v209, v20
	v_cvt_pk_bf16_f32 v18, v18, s0
	v_lshl_add_u64 v[16:17], v[16:17], 1, v[136:137]
	global_store_short v[16:17], v18, off
	v_or_b32_e32 v16, 0x39000, v130
	v_ashrrev_i32_e32 v17, 31, v16
	s_waitcnt vmcnt(62)
	v_add_f32_e32 v20, v26, v104
	v_lshl_add_u64 v[18:19], v[16:17], 2, v[134:135]
	global_store_dword v[18:19], v20, off
	v_mul_f32_e32 v18, v209, v20
	v_cvt_pk_bf16_f32 v18, v18, s0
	v_lshl_add_u64 v[16:17], v[16:17], 1, v[136:137]
	global_store_short v[16:17], v18, off
	v_or_b32_e32 v16, 0x39800, v130
	v_ashrrev_i32_e32 v17, 31, v16
	v_add_f32_e32 v20, v27, v105
	v_lshl_add_u64 v[18:19], v[16:17], 2, v[134:135]
	global_store_dword v[18:19], v20, off
	v_mul_f32_e32 v18, v209, v20
	v_cvt_pk_bf16_f32 v18, v18, s0
	v_lshl_add_u64 v[16:17], v[16:17], 1, v[136:137]
	global_store_short v[16:17], v18, off
	v_or_b32_e32 v16, 0x3c000, v130
	v_ashrrev_i32_e32 v17, 31, v16
	v_add_f32_e32 v20, v28, v106
	v_lshl_add_u64 v[18:19], v[16:17], 2, v[134:135]
	global_store_dword v[18:19], v20, off
	v_mul_f32_e32 v18, v209, v20
	v_cvt_pk_bf16_f32 v18, v18, s0
	v_lshl_add_u64 v[16:17], v[16:17], 1, v[136:137]
	global_store_short v[16:17], v18, off
	v_or_b32_e32 v16, 0x3c800, v130
	v_ashrrev_i32_e32 v17, 31, v16
	v_add_f32_e32 v20, v29, v107
	v_lshl_add_u64 v[18:19], v[16:17], 2, v[134:135]
	global_store_dword v[18:19], v20, off
	v_mul_f32_e32 v18, v209, v20
	v_cvt_pk_bf16_f32 v18, v18, s0
	v_lshl_add_u64 v[16:17], v[16:17], 1, v[136:137]
	global_store_short v[16:17], v18, off
	v_or_b32_e32 v16, 0x3d000, v130
	v_ashrrev_i32_e32 v17, 31, v16
	v_add_f32_e32 v20, v30, v108
	v_lshl_add_u64 v[18:19], v[16:17], 2, v[134:135]
	global_store_dword v[18:19], v20, off
	v_mul_f32_e32 v18, v209, v20
	v_cvt_pk_bf16_f32 v18, v18, s0
	v_lshl_add_u64 v[16:17], v[16:17], 1, v[136:137]
	global_store_short v[16:17], v18, off
	v_or_b32_e32 v16, 0x3d800, v130
	v_ashrrev_i32_e32 v17, 31, v16
	v_add_f32_e32 v20, v31, v109
	v_lshl_add_u64 v[18:19], v[16:17], 2, v[134:135]
	global_store_dword v[18:19], v20, off
	v_mul_f32_e32 v18, v209, v20
	v_cvt_pk_bf16_f32 v18, v18, s0
	v_lshl_add_u64 v[16:17], v[16:17], 1, v[136:137]
	global_store_short v[16:17], v18, off
	v_or_b32_e32 v16, 0x30020, v130
	v_ashrrev_i32_e32 v17, 31, v16
	s_waitcnt vmcnt(47)
	v_add_f32_e32 v0, v0, v36
	v_lshl_add_u64 v[18:19], v[16:17], 2, v[134:135]
	global_store_dword v[18:19], v0, off
	v_mul_f32_e32 v0, v128, v0
	v_cvt_pk_bf16_f32 v0, v0, s0
	v_lshl_add_u64 v[16:17], v[16:17], 1, v[136:137]
	global_store_short v[16:17], v0, off
	v_or_b32_e32 v0, 0x30820, v130
	s_waitcnt vmcnt(48)
	v_add_f32_e32 v18, v1, v37
	v_ashrrev_i32_e32 v1, 31, v0
	v_lshl_add_u64 v[16:17], v[0:1], 2, v[134:135]
	global_store_dword v[16:17], v18, off
	v_mul_f32_e32 v16, v128, v18
	v_cvt_pk_bf16_f32 v16, v16, s0
	v_lshl_add_u64 v[0:1], v[0:1], 1, v[136:137]
	global_store_short v[0:1], v16, off
	v_or_b32_e32 v0, 0x31020, v130
	v_ashrrev_i32_e32 v1, 31, v0
	s_waitcnt vmcnt(49)
	v_add_f32_e32 v2, v2, v38
	v_lshl_add_u64 v[16:17], v[0:1], 2, v[134:135]
	global_store_dword v[16:17], v2, off
	v_mul_f32_e32 v2, v128, v2
	v_cvt_pk_bf16_f32 v2, v2, s0
	v_lshl_add_u64 v[0:1], v[0:1], 1, v[136:137]
	global_store_short v[0:1], v2, off
	v_or_b32_e32 v0, 0x31820, v130
	v_ashrrev_i32_e32 v1, 31, v0
	s_waitcnt vmcnt(50)
	v_add_f32_e32 v16, v3, v39
	v_lshl_add_u64 v[2:3], v[0:1], 2, v[134:135]
	global_store_dword v[2:3], v16, off
	v_mul_f32_e32 v2, v128, v16
	v_cvt_pk_bf16_f32 v2, v2, s0
	v_lshl_add_u64 v[0:1], v[0:1], 1, v[136:137]
	global_store_short v[0:1], v2, off
	v_or_b32_e32 v0, 0x34020, v130
	v_ashrrev_i32_e32 v1, 31, v0
	s_waitcnt vmcnt(51)
	v_add_f32_e32 v4, v4, v40
	v_lshl_add_u64 v[2:3], v[0:1], 2, v[134:135]
	global_store_dword v[2:3], v4, off
	v_mul_f32_e32 v2, v128, v4
	v_cvt_pk_bf16_f32 v2, v2, s0
	v_lshl_add_u64 v[0:1], v[0:1], 1, v[136:137]
	global_store_short v[0:1], v2, off
	v_or_b32_e32 v0, 0x34820, v130
	v_ashrrev_i32_e32 v1, 31, v0
	s_waitcnt vmcnt(52)
	v_add_f32_e32 v4, v5, v41
	v_lshl_add_u64 v[2:3], v[0:1], 2, v[134:135]
	global_store_dword v[2:3], v4, off
	v_mul_f32_e32 v2, v128, v4
	v_cvt_pk_bf16_f32 v2, v2, s0
	v_lshl_add_u64 v[0:1], v[0:1], 1, v[136:137]
	global_store_short v[0:1], v2, off
	v_or_b32_e32 v0, 0x35020, v130
	v_ashrrev_i32_e32 v1, 31, v0
	s_waitcnt vmcnt(53)
	v_add_f32_e32 v4, v6, v42
	v_lshl_add_u64 v[2:3], v[0:1], 2, v[134:135]
	global_store_dword v[2:3], v4, off
	v_mul_f32_e32 v2, v128, v4
	v_cvt_pk_bf16_f32 v2, v2, s0
	v_lshl_add_u64 v[0:1], v[0:1], 1, v[136:137]
	global_store_short v[0:1], v2, off
	v_or_b32_e32 v0, 0x35820, v130
	v_ashrrev_i32_e32 v1, 31, v0
	s_waitcnt vmcnt(54)
	v_add_f32_e32 v4, v7, v43
	v_lshl_add_u64 v[2:3], v[0:1], 2, v[134:135]
	global_store_dword v[2:3], v4, off
	v_mul_f32_e32 v2, v128, v4
	v_cvt_pk_bf16_f32 v2, v2, s0
	v_lshl_add_u64 v[0:1], v[0:1], 1, v[136:137]
	global_store_short v[0:1], v2, off
	v_or_b32_e32 v0, 0x38020, v130
	v_ashrrev_i32_e32 v1, 31, v0
	s_waitcnt vmcnt(55)
	v_add_f32_e32 v4, v8, v44
	v_lshl_add_u64 v[2:3], v[0:1], 2, v[134:135]
	global_store_dword v[2:3], v4, off
	v_mul_f32_e32 v2, v128, v4
	v_cvt_pk_bf16_f32 v2, v2, s0
	v_lshl_add_u64 v[0:1], v[0:1], 1, v[136:137]
	global_store_short v[0:1], v2, off
	v_or_b32_e32 v0, 0x38820, v130
	v_ashrrev_i32_e32 v1, 31, v0
	s_waitcnt vmcnt(56)
	v_add_f32_e32 v4, v9, v45
	v_lshl_add_u64 v[2:3], v[0:1], 2, v[134:135]
	global_store_dword v[2:3], v4, off
	v_mul_f32_e32 v2, v128, v4
	v_cvt_pk_bf16_f32 v2, v2, s0
	v_lshl_add_u64 v[0:1], v[0:1], 1, v[136:137]
	global_store_short v[0:1], v2, off
	v_or_b32_e32 v0, 0x39020, v130
	v_ashrrev_i32_e32 v1, 31, v0
	s_waitcnt vmcnt(57)
	v_add_f32_e32 v4, v10, v46
	v_lshl_add_u64 v[2:3], v[0:1], 2, v[134:135]
	global_store_dword v[2:3], v4, off
	v_mul_f32_e32 v2, v128, v4
	v_cvt_pk_bf16_f32 v2, v2, s0
	v_lshl_add_u64 v[0:1], v[0:1], 1, v[136:137]
	global_store_short v[0:1], v2, off
	v_or_b32_e32 v0, 0x39820, v130
	v_ashrrev_i32_e32 v1, 31, v0
	s_waitcnt vmcnt(58)
	v_add_f32_e32 v4, v11, v47
	v_lshl_add_u64 v[2:3], v[0:1], 2, v[134:135]
	global_store_dword v[2:3], v4, off
	v_mul_f32_e32 v2, v128, v4
	v_cvt_pk_bf16_f32 v2, v2, s0
	v_lshl_add_u64 v[0:1], v[0:1], 1, v[136:137]
	global_store_short v[0:1], v2, off
	v_or_b32_e32 v0, 0x3c020, v130
	v_ashrrev_i32_e32 v1, 31, v0
	s_waitcnt vmcnt(59)
	v_add_f32_e32 v4, v12, v48
	v_lshl_add_u64 v[2:3], v[0:1], 2, v[134:135]
	global_store_dword v[2:3], v4, off
	v_mul_f32_e32 v2, v128, v4
	v_cvt_pk_bf16_f32 v2, v2, s0
	v_lshl_add_u64 v[0:1], v[0:1], 1, v[136:137]
	global_store_short v[0:1], v2, off
	v_or_b32_e32 v0, 0x3c820, v130
	v_ashrrev_i32_e32 v1, 31, v0
	s_waitcnt vmcnt(60)
	v_add_f32_e32 v4, v13, v49
	v_lshl_add_u64 v[2:3], v[0:1], 2, v[134:135]
	global_store_dword v[2:3], v4, off
	v_mul_f32_e32 v2, v128, v4
	v_cvt_pk_bf16_f32 v2, v2, s0
	v_lshl_add_u64 v[0:1], v[0:1], 1, v[136:137]
	global_store_short v[0:1], v2, off
	v_or_b32_e32 v0, 0x3d020, v130
	v_ashrrev_i32_e32 v1, 31, v0
	s_waitcnt vmcnt(61)
	v_add_f32_e32 v4, v14, v50
	v_lshl_add_u64 v[2:3], v[0:1], 2, v[134:135]
	global_store_dword v[2:3], v4, off
	v_mul_f32_e32 v2, v128, v4
	v_cvt_pk_bf16_f32 v2, v2, s0
	v_lshl_add_u64 v[0:1], v[0:1], 1, v[136:137]
	global_store_short v[0:1], v2, off
	v_or_b32_e32 v0, 0x3d820, v130
	v_ashrrev_i32_e32 v1, 31, v0
	s_waitcnt vmcnt(62)
	v_add_f32_e32 v4, v15, v51
	v_lshl_add_u64 v[2:3], v[0:1], 2, v[134:135]
	global_store_dword v[2:3], v4, off
	v_mul_f32_e32 v2, v128, v4
	v_cvt_pk_bf16_f32 v2, v2, s0
	v_lshl_add_u64 v[0:1], v[0:1], 1, v[136:137]
	global_store_short v[0:1], v2, off
	v_add_u32_e32 v206, s46, v206
	v_add_u32_e32 v208, s46, v208
	v_cmp_le_i32_e64 s[40:41], s51, v206
	s_and_b64 vcc, exec, s[40:41]
	s_cbranch_vccz .LBB0_707

.LBB0_715:
	s_add_i32 s16, s22, s33
	s_cmpk_gt_i32 s16, 0x7f
	s_mov_b64 s[30:31], -1
	s_cbranch_scc1 .LBB0_714
	s_ashr_i32 s30, s16, 31
	s_lshr_b32 s30, s30, 25
	s_add_i32 s30, s16, s30
	s_ashr_i32 s61, s30, 7
	s_and_b32 s30, s30, 0xffffff80
	s_lshl_b32 s31, s61, 3
	s_sub_i32 s30, s16, s30
	s_sub_i32 s34, 8, s31
	s_cmpk_gt_i32 s16, 0x7f
	s_cselect_b32 s16, s34, 8
	s_abs_i32 s34, s16
	v_cvt_f32_u32_e32 v0, s34
	s_sub_i32 s41, 0, s34
	s_abs_i32 s35, s30
	s_xor_b32 s40, s30, s16
	v_rcp_iflag_f32_e32 v0, v0
	s_ashr_i32 s40, s40, 31
	v_mov_b32_e32 v10, v204
	v_mul_f32_e32 v0, 0x4f7ffffe, v0
	v_cvt_u32_f32_e32 v0, v0
	v_ashrrev_i32_e32 v1, 6, v10
	v_lshlrev_b32_e32 v3, 9, v10
	v_and_b32_e32 v3, 0x7800, v3
	v_readfirstlane_b32 s42, v0
	s_mul_i32 s41, s41, s42
	s_mul_hi_u32 s41, s42, s41
	s_add_i32 s42, s42, s41
	s_mul_hi_u32 s41, s35, s42
	s_mul_i32 s42, s41, s34
	s_sub_i32 s35, s35, s42
	s_add_i32 s43, s41, 1
	s_sub_i32 s42, s35, s34
	s_cmp_ge_u32 s35, s34
	s_cselect_b32 s41, s43, s41
	s_cselect_b32 s35, s42, s35
	s_add_i32 s42, s41, 1
	s_cmp_ge_u32 s35, s34
	s_cselect_b32 s34, s42, s41
	s_xor_b32 s34, s34, s40
	s_sub_i32 s34, s34, s40
	s_mul_i32 s62, s16, s34
	s_sub_i32 s55, s30, s62
	s_add_i32 s55, s55, s31
	s_lshl_b32 s16, s55, 6
	s_add_i32 s40, s16, 0x2000
	s_ashr_i32 s41, s40, 31
	v_bfe_u32 v0, v10, 4, 2
	s_lshl_b64 s[30:31], s[40:41], 11
	s_lshl_b64 s[40:41], s[40:41], 12
	v_bitop3_b32 v0, v0, v10, 3 bitop3:0x78
	s_add_u32 s40, s50, s40
	v_lshlrev_b32_e32 v2, 3, v0
	v_lshlrev_b32_e32 v0, 15, v1
	v_lshlrev_b32_e32 v4, 16, v1
	v_lshlrev_b32_e32 v1, 10, v1
	s_addc_u32 s41, s51, s41
	s_ashr_i32 s35, s34, 31
	v_or3_b32 v0, v3, v0, v2
	v_add_u32_e32 v40, 32, v1
	s_lshl_b64 s[42:43], s[34:35], 19
	v_or3_b32 v2, v3, v4, v2
	v_add_u32_e32 v41, v40, v1
	v_ashrrev_i32_e32 v1, 31, v0
	s_add_u32 s44, s47, s42
	v_add_u32_e32 v8, 0x1000, v41
	v_lshlrev_b64 v[0:1], 1, v[0:1]
	v_ashrrev_i32_e32 v3, 31, v2
	v_readfirstlane_b32 s35, v40
	s_addc_u32 s45, s49, s43
	v_lshl_add_u64 v[4:5], s[40:41], 0, v[0:1]
	v_lshlrev_b64 v[2:3], 1, v[2:3]
	s_mov_b32 m0, s35
	v_readfirstlane_b32 s35, v8
	v_add_u32_e32 v11, 0x1400, v41
	v_lshl_add_u64 v[6:7], s[44:45], 0, v[2:3]
	s_mov_b32 m0, s35
	v_readfirstlane_b32 s35, v11
	v_add_u32_e32 v11, 0x3000, v40
	v_lshl_add_u64 v[8:9], v[6:7], 0, s[6:7]
	s_mov_b32 m0, s35
	v_readfirstlane_b32 s35, v11
	v_add_u32_e32 v11, 0x4000, v41
	v_lshl_add_u64 v[8:9], v[4:5], 0, 64
	s_mov_b32 m0, s35
	v_readfirstlane_b32 s35, v11
	v_add_u32_e32 v11, 0x4400, v41
	v_lshl_add_u64 v[8:9], v[6:7], 0, 64
	s_mov_b32 m0, s35
	v_readfirstlane_b32 s35, v11
	v_lshl_add_u64 v[8:9], v[6:7], 0, s[8:9]
	s_mov_b32 m0, s35
	v_lshl_add_u64 v[4:5], v[4:5], 0, s[10:11]
	v_add_u32_e32 v8, 0x6000, v40
	s_add_u32 s40, s94, s42
	v_readfirstlane_b32 s35, v8
	v_add_u32_e32 v8, 0x7000, v41
	s_mov_b32 m0, s35
	v_readfirstlane_b32 s35, v8
	v_lshl_add_u64 v[4:5], v[6:7], 0, s[10:11]
	s_mov_b32 m0, s35
	s_addc_u32 s41, s95, s43
	v_lshl_add_u64 v[4:5], v[6:7], 0, s[12:13]
	v_add_u32_e32 v6, 0x7400, v41
	v_lshl_add_u64 v[32:33], s[40:41], 0, v[2:3]
	v_readfirstlane_b32 s35, v6
	s_mov_b32 m0, s35
	s_sub_i32 s40, s48, s62
	s_mulk_i32 s61, 0x78
	s_sub_i32 s40, s40, s61
	s_lshl_b32 s40, s40, 6
	v_and_b32_e32 v4, 31, v10
	v_lshrrev_b32_e32 v6, 2, v10
	s_addk_i32 s40, 0x2000
	v_and_or_b32 v4, v6, s54, v4
	s_ashr_i32 s41, s40, 31
	v_bfe_u32 v5, v10, 5, 1
	v_lshlrev_b32_e32 v42, 6, v4
	v_lshlrev_b32_e32 v4, 6, v10
	s_lshl_b64 s[40:41], s[40:41], 12
	v_bfe_u32 v7, v10, 2, 2
	v_and_b32_e32 v43, 0x17c0, v4
	v_bitop3_b32 v4, v5, v6, 3 bitop3:0x78
	s_add_u32 s40, s94, s40
	v_lshlrev_b32_e32 v44, 4, v4
	v_bitop3_b32 v4, v5, v7, 2 bitop3:0x36
	s_addc_u32 s41, s95, s41
	v_mov_b32_e32 v16, 0
	s_mov_b32 s60, 0
	s_mov_b32 s35, 1
	v_lshlrev_b32_e32 v45, 4, v4
	v_lshl_add_u64 v[34:35], s[40:41], 0, v[0:1]
	s_mov_b64 s[40:41], 0
	v_mov_b32_e32 v17, v16
	v_mov_b32_e32 v18, v16
	v_mov_b32_e32 v19, v16
	v_mov_b32_e32 v20, v16
	v_mov_b32_e32 v21, v16
	v_mov_b32_e32 v22, v16
	v_mov_b32_e32 v23, v16
	v_mov_b32_e32 v24, v16
	v_mov_b32_e32 v25, v16
	v_mov_b32_e32 v26, v16
	v_mov_b32_e32 v27, v16
	v_mov_b32_e32 v28, v16
	v_mov_b32_e32 v29, v16
	v_mov_b32_e32 v30, v16
	v_mov_b32_e32 v31, v16
	v_mov_b32_e32 v0, v16
	v_mov_b32_e32 v1, v16
	v_mov_b32_e32 v2, v16
	v_mov_b32_e32 v3, v16
	v_mov_b32_e32 v4, v16
	v_mov_b32_e32 v5, v16
	v_mov_b32_e32 v6, v16
	v_mov_b32_e32 v7, v16
	v_mov_b32_e32 v8, v16
	v_mov_b32_e32 v9, v16
	v_mov_b32_e32 v10, v16
	v_mov_b32_e32 v11, v16
	v_mov_b32_e32 v12, v16
	v_mov_b32_e32 v13, v16
	v_mov_b32_e32 v14, v16
	v_mov_b32_e32 v15, v16
	v_add3_u32 v184, v42, v44, 32
	v_add3_u32 v185, v42, v45, 32
	v_add_u32_e32 v186, 0x1020, v43
	v_add_u32_e32 v187, v186, v45
	v_add_u32_e32 v186, v186, v44
	v_subrev_u32_e32 v188, s94, v34
	v_subrev_u32_e32 v189, s94, v32
	v_add_u32_e32 v188, 0x15c88000, v188
	v_add_u32_e32 v189, 0x18a88000, v189
	v_add_u32_e32 v190, 0x10000, v189
	v_readfirstlane_b32 s80, v40
	v_readfirstlane_b32 s81, v41
	s_add_u32 s81, s81, 0x1000
	s_mov_b64 s[76:77], s[94:95]
	s_add_u32 s78, s94, 64
	s_addc_u32 s79, s95, 0
	v_bfe_u32 v191, v204, 2, 4
	v_lshlrev_b32_e32 v191, 7, v191
	s_mov_b32 s83, 0
	s_movk_i32 s84, 0x800
	v_xad_u32 v192, s83, v191, v189
	v_xad_u32 v193, s84, v191, v190
	s_add_u32 m0, s80, 0x0
	s_nop 0
	global_load_lds_dwordx4 v188, s[76:77]
	s_add_u32 m0, s80, 0x3000
	s_nop 0
	global_load_lds_dwordx4 v188, s[78:79]
	s_add_u32 m0, s81, 0x0
	s_nop 0
	global_load_lds_dwordx4 v192, s[94:95]
	s_add_u32 m0, s81, 0x2fc0
	s_nop 0
	global_load_lds_dwordx4 v192, s[94:95] offset:64
	s_add_u32 m0, s81, 0x400
	s_nop 0
	global_load_lds_dwordx4 v193, s[94:95]
	s_add_u32 m0, s81, 0x33c0
	s_nop 0
	global_load_lds_dwordx4 v193, s[94:95] offset:64
	s_add_u32 s83, s83, 0x80
	s_xor_b32 s84, s83, 0x800
	s_add_u32 s76, s76, 128
	s_addc_u32 s77, s77, 0
	s_add_u32 s78, s78, 128
	s_addc_u32 s79, s79, 0
	v_xad_u32 v192, s83, v191, v189
	v_xad_u32 v193, s84, v191, v190
	s_add_u32 m0, s80, 0x6000
	s_nop 0
	global_load_lds_dwordx4 v188, s[76:77]
	s_add_u32 m0, s80, 0x9000
	s_nop 0
	global_load_lds_dwordx4 v188, s[78:79]
	s_add_u32 m0, s81, 0x6000
	s_nop 0
	global_load_lds_dwordx4 v192, s[94:95]
	s_add_u32 m0, s81, 0x8fc0
	s_nop 0
	global_load_lds_dwordx4 v192, s[94:95] offset:64
	s_add_u32 m0, s81, 0x6400
	s_nop 0
	global_load_lds_dwordx4 v193, s[94:95]
	s_add_u32 m0, s81, 0x93c0
	s_nop 0
	global_load_lds_dwordx4 v193, s[94:95] offset:64
	s_add_u32 s83, s83, 0x80
	s_xor_b32 s84, s83, 0x800
	s_add_u32 s76, s76, 128
	s_addc_u32 s77, s77, 0
	s_add_u32 s78, s78, 128
	s_addc_u32 s79, s79, 0
	v_xad_u32 v192, s83, v191, v189
	v_xad_u32 v193, s84, v191, v190
	s_add_u32 m0, s80, 0xc000
	s_nop 0
	global_load_lds_dwordx4 v188, s[76:77]
	s_add_u32 m0, s80, 0xf000
	s_nop 0
	global_load_lds_dwordx4 v188, s[78:79]
	s_add_u32 m0, s81, 0xc000
	s_nop 0
	global_load_lds_dwordx4 v192, s[94:95]
	s_add_u32 m0, s81, 0xefc0
	s_nop 0
	global_load_lds_dwordx4 v192, s[94:95] offset:64
	s_add_u32 m0, s81, 0xc400
	s_nop 0
	global_load_lds_dwordx4 v193, s[94:95]
	s_add_u32 m0, s81, 0xf3c0
	s_nop 0
	global_load_lds_dwordx4 v193, s[94:95] offset:64
	s_add_u32 s83, s83, 0x80
	s_xor_b32 s84, s83, 0x800
	s_add_u32 s76, s76, 128
	s_addc_u32 s77, s77, 0
	s_add_u32 s78, s78, 128
	s_addc_u32 s79, s79, 0
	s_waitcnt vmcnt(13)
	s_barrier
	ds_read_b128 v[160:163], v186 offset:0
	ds_read_b128 v[164:167], v186 offset:2048
	ds_read_b128 v[168:171], v184 offset:0
	s_waitcnt lgkmcnt(0)
	s_setprio 1
	v_mfma_f32_32x32x16_bf16 v[16:31], v[168:171], v[160:163], v[16:31]
	v_mfma_f32_32x32x16_bf16 v[0:15], v[168:171], v[164:167], v[0:15]
	s_setprio 0
	ds_read_b128 v[172:175], v187 offset:0
	ds_read_b128 v[176:179], v187 offset:2048
	ds_read_b128 v[180:183], v185 offset:0
	s_waitcnt vmcnt(12) lgkmcnt(0)
	s_barrier
	ds_read_b128 v[160:163], v186 offset:12288
	ds_read_b128 v[164:167], v186 offset:14336
	ds_read_b128 v[168:171], v184 offset:12288
	s_setprio 1
	v_mfma_f32_32x32x16_bf16 v[16:31], v[180:183], v[172:175], v[16:31]
	v_mfma_f32_32x32x16_bf16 v[0:15], v[180:183], v[176:179], v[0:15]
	s_setprio 0
	s_waitcnt lgkmcnt(0)
	s_setprio 1
	v_mfma_f32_32x32x16_bf16 v[16:31], v[168:171], v[160:163], v[16:31]
	v_mfma_f32_32x32x16_bf16 v[0:15], v[168:171], v[164:167], v[0:15]
	s_setprio 0
	ds_read_b128 v[172:175], v187 offset:12288
	ds_read_b128 v[176:179], v187 offset:14336
	ds_read_b128 v[180:183], v185 offset:12288
	s_waitcnt vmcnt(7) lgkmcnt(0)
	s_barrier
	ds_read_b128 v[160:163], v186 offset:24576
	ds_read_b128 v[164:167], v186 offset:26624
	ds_read_b128 v[168:171], v184 offset:24576
	s_setprio 1
	v_mfma_f32_32x32x16_bf16 v[16:31], v[180:183], v[172:175], v[16:31]
	v_mfma_f32_32x32x16_bf16 v[0:15], v[180:183], v[176:179], v[0:15]
	s_setprio 0
	s_add_u32 m0, s80, 0x0
	s_nop 0
	global_load_lds_dwordx4 v188, s[76:77]
	s_add_u32 m0, s80, 0x3000
	s_nop 0
	global_load_lds_dwordx4 v188, s[78:79]
	s_waitcnt lgkmcnt(0)
	s_setprio 1
	v_mfma_f32_32x32x16_bf16 v[16:31], v[168:171], v[160:163], v[16:31]
	v_mfma_f32_32x32x16_bf16 v[0:15], v[168:171], v[164:167], v[0:15]
	s_setprio 0
	ds_read_b128 v[172:175], v187 offset:24576
	ds_read_b128 v[176:179], v187 offset:26624
	ds_read_b128 v[180:183], v185 offset:24576
	v_xad_u32 v192, s83, v191, v189
	v_xad_u32 v193, s84, v191, v190
	s_add_u32 m0, s81, 0x0
	s_nop 0
	global_load_lds_dwordx4 v192, s[94:95]
	s_add_u32 m0, s81, 0x2fc0
	s_nop 0
	global_load_lds_dwordx4 v192, s[94:95] offset:64
	s_add_u32 m0, s81, 0x400
	s_nop 0
	global_load_lds_dwordx4 v193, s[94:95]
	s_add_u32 m0, s81, 0x33c0
	s_nop 0
	global_load_lds_dwordx4 v193, s[94:95] offset:64
	s_add_u32 s83, s83, 0x80
	s_xor_b32 s84, s83, 0x800
	s_add_u32 s76, s76, 128
	s_addc_u32 s77, s77, 0
	s_add_u32 s78, s78, 128
	s_addc_u32 s79, s79, 0
	s_waitcnt vmcnt(12) lgkmcnt(0)
	s_barrier
	ds_read_b128 v[160:163], v186 offset:36864
	ds_read_b128 v[164:167], v186 offset:38912
	ds_read_b128 v[168:171], v184 offset:36864
	s_setprio 1
	v_mfma_f32_32x32x16_bf16 v[16:31], v[180:183], v[172:175], v[16:31]
	v_mfma_f32_32x32x16_bf16 v[0:15], v[180:183], v[176:179], v[0:15]
	s_setprio 0
	s_waitcnt lgkmcnt(0)
	s_setprio 1
	v_mfma_f32_32x32x16_bf16 v[16:31], v[168:171], v[160:163], v[16:31]
	v_mfma_f32_32x32x16_bf16 v[0:15], v[168:171], v[164:167], v[0:15]
	s_setprio 0
	ds_read_b128 v[172:175], v187 offset:36864
	ds_read_b128 v[176:179], v187 offset:38912
	ds_read_b128 v[180:183], v185 offset:36864
	s_waitcnt vmcnt(7) lgkmcnt(0)
	s_barrier
	ds_read_b128 v[160:163], v186 offset:49152
	ds_read_b128 v[164:167], v186 offset:51200
	ds_read_b128 v[168:171], v184 offset:49152
	s_setprio 1
	v_mfma_f32_32x32x16_bf16 v[16:31], v[180:183], v[172:175], v[16:31]
	v_mfma_f32_32x32x16_bf16 v[0:15], v[180:183], v[176:179], v[0:15]
	s_setprio 0
	s_add_u32 m0, s80, 0x6000
	s_nop 0
	global_load_lds_dwordx4 v188, s[76:77]
	s_add_u32 m0, s80, 0x9000
	s_nop 0
	global_load_lds_dwordx4 v188, s[78:79]
	s_waitcnt lgkmcnt(0)
	s_setprio 1
	v_mfma_f32_32x32x16_bf16 v[16:31], v[168:171], v[160:163], v[16:31]
	v_mfma_f32_32x32x16_bf16 v[0:15], v[168:171], v[164:167], v[0:15]
	s_setprio 0
	ds_read_b128 v[172:175], v187 offset:49152
	ds_read_b128 v[176:179], v187 offset:51200
	ds_read_b128 v[180:183], v185 offset:49152
	v_xad_u32 v192, s83, v191, v189
	v_xad_u32 v193, s84, v191, v190
	s_add_u32 m0, s81, 0x6000
	s_nop 0
	global_load_lds_dwordx4 v192, s[94:95]
	s_add_u32 m0, s81, 0x8fc0
	s_nop 0
	global_load_lds_dwordx4 v192, s[94:95] offset:64
	s_add_u32 m0, s81, 0x6400
	s_nop 0
	global_load_lds_dwordx4 v193, s[94:95]
	s_add_u32 m0, s81, 0x93c0
	s_nop 0
	global_load_lds_dwordx4 v193, s[94:95] offset:64
	s_add_u32 s83, s83, 0x80
	s_xor_b32 s84, s83, 0x800
	s_add_u32 s76, s76, 128
	s_addc_u32 s77, s77, 0
	s_add_u32 s78, s78, 128
	s_addc_u32 s79, s79, 0
	s_waitcnt vmcnt(12) lgkmcnt(0)
	s_barrier
	ds_read_b128 v[160:163], v186 offset:61440
	ds_read_b128 v[164:167], v186 offset:63488
	ds_read_b128 v[168:171], v184 offset:61440
	s_setprio 1
	v_mfma_f32_32x32x16_bf16 v[16:31], v[180:183], v[172:175], v[16:31]
	v_mfma_f32_32x32x16_bf16 v[0:15], v[180:183], v[176:179], v[0:15]
	s_setprio 0
	s_waitcnt lgkmcnt(0)
	s_setprio 1
	v_mfma_f32_32x32x16_bf16 v[16:31], v[168:171], v[160:163], v[16:31]
	v_mfma_f32_32x32x16_bf16 v[0:15], v[168:171], v[164:167], v[0:15]
	s_setprio 0
	ds_read_b128 v[172:175], v187 offset:61440
	ds_read_b128 v[176:179], v187 offset:63488
	ds_read_b128 v[180:183], v185 offset:61440
	s_mov_b32 s82, 9
.Lp5s_kloop:
	s_waitcnt vmcnt(6) lgkmcnt(0)
	s_barrier
	ds_read_b128 v[160:163], v186 offset:0
	ds_read_b128 v[164:167], v186 offset:2048
	ds_read_b128 v[168:171], v184 offset:0
	s_setprio 1
	v_mfma_f32_32x32x16_bf16 v[16:31], v[180:183], v[172:175], v[16:31]
	v_mfma_f32_32x32x16_bf16 v[0:15], v[180:183], v[176:179], v[0:15]
	s_setprio 0
	s_add_u32 m0, s80, 0xc000
	s_nop 0
	global_load_lds_dwordx4 v188, s[76:77]
	s_add_u32 m0, s80, 0xf000
	s_nop 0
	global_load_lds_dwordx4 v188, s[78:79]
	s_waitcnt lgkmcnt(0)
	s_setprio 1
	v_mfma_f32_32x32x16_bf16 v[16:31], v[168:171], v[160:163], v[16:31]
	v_mfma_f32_32x32x16_bf16 v[0:15], v[168:171], v[164:167], v[0:15]
	s_setprio 0
	ds_read_b128 v[172:175], v187 offset:0
	ds_read_b128 v[176:179], v187 offset:2048
	ds_read_b128 v[180:183], v185 offset:0
	v_xad_u32 v192, s83, v191, v189
	v_xad_u32 v193, s84, v191, v190
	s_add_u32 m0, s81, 0xc000
	s_nop 0
	global_load_lds_dwordx4 v192, s[94:95]
	s_add_u32 m0, s81, 0xefc0
	s_nop 0
	global_load_lds_dwordx4 v192, s[94:95] offset:64
	s_add_u32 m0, s81, 0xc400
	s_nop 0
	global_load_lds_dwordx4 v193, s[94:95]
	s_add_u32 m0, s81, 0xf3c0
	s_nop 0
	global_load_lds_dwordx4 v193, s[94:95] offset:64
	s_add_u32 s83, s83, 0x80
	s_xor_b32 s84, s83, 0x800
	s_add_u32 s76, s76, 128
	s_addc_u32 s77, s77, 0
	s_add_u32 s78, s78, 128
	s_addc_u32 s79, s79, 0
	s_waitcnt lgkmcnt(0)
	s_barrier
	ds_read_b128 v[160:163], v186 offset:12288
	ds_read_b128 v[164:167], v186 offset:14336
	ds_read_b128 v[168:171], v184 offset:12288
	s_setprio 1
	v_mfma_f32_32x32x16_bf16 v[16:31], v[180:183], v[172:175], v[16:31]
	v_mfma_f32_32x32x16_bf16 v[0:15], v[180:183], v[176:179], v[0:15]
	s_setprio 0
	s_waitcnt lgkmcnt(0)
	s_setprio 1
	v_mfma_f32_32x32x16_bf16 v[16:31], v[168:171], v[160:163], v[16:31]
	v_mfma_f32_32x32x16_bf16 v[0:15], v[168:171], v[164:167], v[0:15]
	s_setprio 0
	ds_read_b128 v[172:175], v187 offset:12288
	ds_read_b128 v[176:179], v187 offset:14336
	ds_read_b128 v[180:183], v185 offset:12288
	s_waitcnt vmcnt(6) lgkmcnt(0)
	s_barrier
	ds_read_b128 v[160:163], v186 offset:24576
	ds_read_b128 v[164:167], v186 offset:26624
	ds_read_b128 v[168:171], v184 offset:24576
	s_setprio 1
	v_mfma_f32_32x32x16_bf16 v[16:31], v[180:183], v[172:175], v[16:31]
	v_mfma_f32_32x32x16_bf16 v[0:15], v[180:183], v[176:179], v[0:15]
	s_setprio 0
	s_add_u32 m0, s80, 0x0
	s_nop 0
	global_load_lds_dwordx4 v188, s[76:77]
	s_add_u32 m0, s80, 0x3000
	s_nop 0
	global_load_lds_dwordx4 v188, s[78:79]
	s_waitcnt lgkmcnt(0)
	s_setprio 1
	v_mfma_f32_32x32x16_bf16 v[16:31], v[168:171], v[160:163], v[16:31]
	v_mfma_f32_32x32x16_bf16 v[0:15], v[168:171], v[164:167], v[0:15]
	s_setprio 0
	ds_read_b128 v[172:175], v187 offset:24576
	ds_read_b128 v[176:179], v187 offset:26624
	ds_read_b128 v[180:183], v185 offset:24576
	v_xad_u32 v192, s83, v191, v189
	v_xad_u32 v193, s84, v191, v190
	s_add_u32 m0, s81, 0x0
	s_nop 0
	global_load_lds_dwordx4 v192, s[94:95]
	s_add_u32 m0, s81, 0x2fc0
	s_nop 0
	global_load_lds_dwordx4 v192, s[94:95] offset:64
	s_add_u32 m0, s81, 0x400
	s_nop 0
	global_load_lds_dwordx4 v193, s[94:95]
	s_add_u32 m0, s81, 0x33c0
	s_nop 0
	global_load_lds_dwordx4 v193, s[94:95] offset:64
	s_add_u32 s83, s83, 0x80
	s_xor_b32 s84, s83, 0x800
	s_add_u32 s76, s76, 128
	s_addc_u32 s77, s77, 0
	s_add_u32 s78, s78, 128
	s_addc_u32 s79, s79, 0
	s_waitcnt lgkmcnt(0)
	s_barrier
	ds_read_b128 v[160:163], v186 offset:36864
	ds_read_b128 v[164:167], v186 offset:38912
	ds_read_b128 v[168:171], v184 offset:36864
	s_setprio 1
	v_mfma_f32_32x32x16_bf16 v[16:31], v[180:183], v[172:175], v[16:31]
	v_mfma_f32_32x32x16_bf16 v[0:15], v[180:183], v[176:179], v[0:15]
	s_setprio 0
	s_waitcnt lgkmcnt(0)
	s_setprio 1
	v_mfma_f32_32x32x16_bf16 v[16:31], v[168:171], v[160:163], v[16:31]
	v_mfma_f32_32x32x16_bf16 v[0:15], v[168:171], v[164:167], v[0:15]
	s_setprio 0
	ds_read_b128 v[172:175], v187 offset:36864
	ds_read_b128 v[176:179], v187 offset:38912
	ds_read_b128 v[180:183], v185 offset:36864
	s_waitcnt vmcnt(6) lgkmcnt(0)
	s_barrier
	ds_read_b128 v[160:163], v186 offset:49152
	ds_read_b128 v[164:167], v186 offset:51200
	ds_read_b128 v[168:171], v184 offset:49152
	s_setprio 1
	v_mfma_f32_32x32x16_bf16 v[16:31], v[180:183], v[172:175], v[16:31]
	v_mfma_f32_32x32x16_bf16 v[0:15], v[180:183], v[176:179], v[0:15]
	s_setprio 0
	s_add_u32 m0, s80, 0x6000
	s_nop 0
	global_load_lds_dwordx4 v188, s[76:77]
	s_add_u32 m0, s80, 0x9000
	s_nop 0
	global_load_lds_dwordx4 v188, s[78:79]
	s_waitcnt lgkmcnt(0)
	s_setprio 1
	v_mfma_f32_32x32x16_bf16 v[16:31], v[168:171], v[160:163], v[16:31]
	v_mfma_f32_32x32x16_bf16 v[0:15], v[168:171], v[164:167], v[0:15]
	s_setprio 0
	ds_read_b128 v[172:175], v187 offset:49152
	ds_read_b128 v[176:179], v187 offset:51200
	ds_read_b128 v[180:183], v185 offset:49152
	v_xad_u32 v192, s83, v191, v189
	v_xad_u32 v193, s84, v191, v190
	s_add_u32 m0, s81, 0x6000
	s_nop 0
	global_load_lds_dwordx4 v192, s[94:95]
	s_add_u32 m0, s81, 0x8fc0
	s_nop 0
	global_load_lds_dwordx4 v192, s[94:95] offset:64
	s_add_u32 m0, s81, 0x6400
	s_nop 0
	global_load_lds_dwordx4 v193, s[94:95]
	s_add_u32 m0, s81, 0x93c0
	s_nop 0
	global_load_lds_dwordx4 v193, s[94:95] offset:64
	s_add_u32 s83, s83, 0x80
	s_xor_b32 s84, s83, 0x800
	s_add_u32 s76, s76, 128
	s_addc_u32 s77, s77, 0
	s_add_u32 s78, s78, 128
	s_addc_u32 s79, s79, 0
	s_waitcnt lgkmcnt(0)
	s_barrier
	ds_read_b128 v[160:163], v186 offset:61440
	ds_read_b128 v[164:167], v186 offset:63488
	ds_read_b128 v[168:171], v184 offset:61440
	s_setprio 1
	v_mfma_f32_32x32x16_bf16 v[16:31], v[180:183], v[172:175], v[16:31]
	v_mfma_f32_32x32x16_bf16 v[0:15], v[180:183], v[176:179], v[0:15]
	s_setprio 0
	s_waitcnt lgkmcnt(0)
	s_setprio 1
	v_mfma_f32_32x32x16_bf16 v[16:31], v[168:171], v[160:163], v[16:31]
	v_mfma_f32_32x32x16_bf16 v[0:15], v[168:171], v[164:167], v[0:15]
	s_setprio 0
	ds_read_b128 v[172:175], v187 offset:61440
	ds_read_b128 v[176:179], v187 offset:63488
	ds_read_b128 v[180:183], v185 offset:61440
	s_sub_u32 s82, s82, 1
	s_cmp_lg_u32 s82, 0
	s_cbranch_scc1 .Lp5s_kloop
	s_waitcnt vmcnt(6) lgkmcnt(0)
	s_barrier
	ds_read_b128 v[160:163], v186 offset:0
	ds_read_b128 v[164:167], v186 offset:2048
	ds_read_b128 v[168:171], v184 offset:0
	s_setprio 1
	v_mfma_f32_32x32x16_bf16 v[16:31], v[180:183], v[172:175], v[16:31]
	v_mfma_f32_32x32x16_bf16 v[0:15], v[180:183], v[176:179], v[0:15]
	s_setprio 0
	s_waitcnt lgkmcnt(0)
	s_setprio 1
	v_mfma_f32_32x32x16_bf16 v[16:31], v[168:171], v[160:163], v[16:31]
	v_mfma_f32_32x32x16_bf16 v[0:15], v[168:171], v[164:167], v[0:15]
	s_setprio 0
	ds_read_b128 v[172:175], v187 offset:0
	ds_read_b128 v[176:179], v187 offset:2048
	ds_read_b128 v[180:183], v185 offset:0
	s_waitcnt lgkmcnt(0)
	s_barrier
	ds_read_b128 v[160:163], v186 offset:12288
	ds_read_b128 v[164:167], v186 offset:14336
	ds_read_b128 v[168:171], v184 offset:12288
	s_setprio 1
	v_mfma_f32_32x32x16_bf16 v[16:31], v[180:183], v[172:175], v[16:31]
	v_mfma_f32_32x32x16_bf16 v[0:15], v[180:183], v[176:179], v[0:15]
	s_setprio 0
	s_waitcnt lgkmcnt(0)
	s_setprio 1
	v_mfma_f32_32x32x16_bf16 v[16:31], v[168:171], v[160:163], v[16:31]
	v_mfma_f32_32x32x16_bf16 v[0:15], v[168:171], v[164:167], v[0:15]
	s_setprio 0
	ds_read_b128 v[172:175], v187 offset:12288
	ds_read_b128 v[176:179], v187 offset:14336
	ds_read_b128 v[180:183], v185 offset:12288
	s_waitcnt vmcnt(0) lgkmcnt(0)
	s_barrier
	ds_read_b128 v[160:163], v186 offset:24576
	ds_read_b128 v[164:167], v186 offset:26624
	ds_read_b128 v[168:171], v184 offset:24576
	s_setprio 1
	v_mfma_f32_32x32x16_bf16 v[16:31], v[180:183], v[172:175], v[16:31]
	v_mfma_f32_32x32x16_bf16 v[0:15], v[180:183], v[176:179], v[0:15]
	s_setprio 0
	s_waitcnt lgkmcnt(0)
	s_setprio 1
	v_mfma_f32_32x32x16_bf16 v[16:31], v[168:171], v[160:163], v[16:31]
	v_mfma_f32_32x32x16_bf16 v[0:15], v[168:171], v[164:167], v[0:15]
	s_setprio 0
	ds_read_b128 v[172:175], v187 offset:24576
	ds_read_b128 v[176:179], v187 offset:26624
	ds_read_b128 v[180:183], v185 offset:24576
	s_waitcnt lgkmcnt(0)
	s_barrier
	ds_read_b128 v[160:163], v186 offset:36864
	ds_read_b128 v[164:167], v186 offset:38912
	ds_read_b128 v[168:171], v184 offset:36864
	s_setprio 1
	v_mfma_f32_32x32x16_bf16 v[16:31], v[180:183], v[172:175], v[16:31]
	v_mfma_f32_32x32x16_bf16 v[0:15], v[180:183], v[176:179], v[0:15]
	s_setprio 0
	s_waitcnt lgkmcnt(0)
	s_setprio 1
	v_mfma_f32_32x32x16_bf16 v[16:31], v[168:171], v[160:163], v[16:31]
	v_mfma_f32_32x32x16_bf16 v[0:15], v[168:171], v[164:167], v[0:15]
	s_setprio 0
	ds_read_b128 v[172:175], v187 offset:36864
	ds_read_b128 v[176:179], v187 offset:38912
	ds_read_b128 v[180:183], v185 offset:36864
	s_waitcnt lgkmcnt(0)
	s_setprio 1
	v_mfma_f32_32x32x16_bf16 v[16:31], v[180:183], v[172:175], v[16:31]
	v_mfma_f32_32x32x16_bf16 v[0:15], v[180:183], v[176:179], v[0:15]
	s_setprio 0
	s_branch .LBB0_713

	.amdhsa_kernel _Z4mega6Paramsiii
		.amdhsa_group_segment_fixed_size 32
		.amdhsa_private_segment_fixed_size 0
		.amdhsa_kernarg_size 544
		.amdhsa_user_sgpr_count 2
		.amdhsa_user_sgpr_dispatch_ptr 0
		.amdhsa_user_sgpr_queue_ptr 0
		.amdhsa_user_sgpr_kernarg_segment_ptr 1
		.amdhsa_user_sgpr_dispatch_id 0
		.amdhsa_user_sgpr_kernarg_preload_length 0
		.amdhsa_user_sgpr_kernarg_preload_offset 0
		.amdhsa_user_sgpr_private_segment_size 0
		.amdhsa_uses_dynamic_stack 0
		.amdhsa_enable_private_segment 0
		.amdhsa_system_sgpr_workgroup_id_x 1
		.amdhsa_system_sgpr_workgroup_id_y 0
		.amdhsa_system_sgpr_workgroup_id_z 0
		.amdhsa_system_sgpr_workgroup_info 0
		.amdhsa_system_vgpr_workitem_id 2
		.amdhsa_next_free_vgpr 256
		.amdhsa_next_free_sgpr 102
		.amdhsa_accum_offset 256
		.amdhsa_reserve_vcc 1
		.amdhsa_float_round_mode_32 0
		.amdhsa_float_round_mode_16_64 0
		.amdhsa_float_denorm_mode_32 3
		.amdhsa_float_denorm_mode_16_64 3
		.amdhsa_dx10_clamp 1
		.amdhsa_ieee_mode 1
		.amdhsa_fp16_overflow 0
		.amdhsa_tg_split 0
		.amdhsa_exception_fp_ieee_invalid_op 0
		.amdhsa_exception_fp_denorm_src 0
		.amdhsa_exception_fp_ieee_div_zero 0
		.amdhsa_exception_fp_ieee_overflow 0
		.amdhsa_exception_fp_ieee_underflow 0
		.amdhsa_exception_fp_ieee_inexact 0
		.amdhsa_exception_int_div_zero 0
	.end_amdhsa_kernel

amdhsa.kernels:
  - .agpr_count:     0
    .args:
      - .offset:         0
        .size:           272
        .value_kind:     by_value
      - .offset:         272
        .size:           4
        .value_kind:     by_value
      - .offset:         276
        .size:           4
        .value_kind:     by_value
      - .offset:         280
        .size:           4
        .value_kind:     by_value
      - .offset:         288
        .size:           4
        .value_kind:     hidden_block_count_x
      - .offset:         292
        .size:           4
        .value_kind:     hidden_block_count_y
      - .offset:         296
        .size:           4
        .value_kind:     hidden_block_count_z
      - .offset:         300
        .size:           2
        .value_kind:     hidden_group_size_x
      - .offset:         302
        .size:           2
        .value_kind:     hidden_group_size_y
      - .offset:         304
        .size:           2
        .value_kind:     hidden_group_size_z
      - .offset:         306
        .size:           2
        .value_kind:     hidden_remainder_x
      - .offset:         308
        .size:           2
        .value_kind:     hidden_remainder_y
      - .offset:         310
        .size:           2
        .value_kind:     hidden_remainder_z
      - .offset:         328
        .size:           8
        .value_kind:     hidden_global_offset_x
      - .offset:         336
        .size:           8
        .value_kind:     hidden_global_offset_y
      - .offset:         344
        .size:           8
        .value_kind:     hidden_global_offset_z
      - .offset:         352
        .size:           2
        .value_kind:     hidden_grid_dims
      - .offset:         376
        .size:           8
        .value_kind:     hidden_multigrid_sync_arg
      - .offset:         408
        .size:           4
        .value_kind:     hidden_dynamic_lds_size
    .group_segment_fixed_size: 32
    .kernarg_segment_align: 8
    .kernarg_segment_size: 544
    .language:       OpenCL C
    .language_version:
      - 2
      - 0
    .max_flat_workgroup_size: 256
    .name:           _Z4mega6Paramsiii
    .private_segment_fixed_size: 0
    .sgpr_count:     108
    .sgpr_spill_count: 10
    .symbol:         _Z4mega6Paramsiii.kd
    .uniform_work_group_size: 1
    .uses_dynamic_stack: false
    .vgpr_count:     256
    .vgpr_spill_count: 0
    .wavefront_size: 64
